# v101 plus the paired vmcnt/lgkmcnt waits before each GEMM pre-MFMA barrier merged into one s_waitcnt
# baseline (speedup 1.0000x reference)
.LBB0_224:
	s_add_u32 s44, s38, 0x100
	s_addc_u32 s45, s39, 0
	s_add_i32 s30, 0, 0x10000
	s_cmp_eq_u32 s73, 12
	s_cselect_b32 s49, s9, s45
	s_cselect_b32 s48, s11, s44
	v_add_u32_e32 v138, s30, v141
	s_cselect_b32 s47, s20, s29
	s_cselect_b32 s46, s21, s27
	s_add_i32 s83, 0, 0x14000
	ds_read_b128 v[148:151], v138
	ds_read_b128 v[152:155], v138 offset:1024
	ds_read_b128 v[156:159], v138 offset:2048
	ds_read_b128 v[160:163], v138 offset:3072
	v_add_u32_e32 v138, s83, v141
	ds_read_b128 v[164:167], v138
	ds_read_b128 v[168:171], v138 offset:1024
	ds_read_b128 v[172:175], v138 offset:2048
	ds_read_b128 v[198:201], v138 offset:3072
	v_lshl_add_u64 v[138:139], s[38:39], 0, v[136:137]
	s_add_i32 m0, s40, 0xc000
	ds_read_b128 v[202:205], v145
	ds_read_b128 v[206:209], v145 offset:1024
	ds_read_b128 v[210:213], v145 offset:2048
	ds_read_b128 v[214:217], v145 offset:3072
	ds_read_b128 v[218:221], v145 offset:4096
	ds_read_b128 v[222:225], v145 offset:5120
	ds_read_b128 v[226:229], v145 offset:6144
	ds_read_b128 v[238:241], v145 offset:7168
	global_load_lds_dwordx4 v[138:139], off
	v_lshl_add_u64 v[138:139], s[38:39], 0, v[134:135]
	s_add_i32 m0, s40, 0xe000
	s_nop 0
	global_load_lds_dwordx4 v[138:139], off
	s_waitcnt vmcnt(8) lgkmcnt(0)
	s_barrier
	s_setprio 1
	v_mfma_f32_16x16x32_bf16 v[124:127], v[148:151], v[202:205], v[124:127]
	v_mfma_f32_16x16x32_bf16 v[120:123], v[156:159], v[202:205], v[120:123]
	v_mfma_f32_16x16x32_bf16 v[116:119], v[148:151], v[210:213], v[116:119]
	v_mfma_f32_16x16x32_bf16 v[112:115], v[156:159], v[210:213], v[112:115]
	v_mfma_f32_16x16x32_bf16 v[108:111], v[148:151], v[218:221], v[108:111]
	v_mfma_f32_16x16x32_bf16 v[104:107], v[156:159], v[218:221], v[104:107]
	v_mfma_f32_16x16x32_bf16 v[100:103], v[148:151], v[226:229], v[100:103]
	v_mfma_f32_16x16x32_bf16 v[96:99], v[156:159], v[226:229], v[96:99]
	v_mfma_f32_16x16x32_bf16 v[124:127], v[152:155], v[206:209], v[124:127]
	v_mfma_f32_16x16x32_bf16 v[120:123], v[160:163], v[206:209], v[120:123]
	v_mfma_f32_16x16x32_bf16 v[116:119], v[152:155], v[214:217], v[116:119]
	v_mfma_f32_16x16x32_bf16 v[112:115], v[160:163], v[214:217], v[112:115]
	v_mfma_f32_16x16x32_bf16 v[108:111], v[152:155], v[222:225], v[108:111]
	v_mfma_f32_16x16x32_bf16 v[104:107], v[160:163], v[222:225], v[104:107]
	v_mfma_f32_16x16x32_bf16 v[100:103], v[152:155], v[238:241], v[100:103]
	v_mfma_f32_16x16x32_bf16 v[96:99], v[160:163], v[238:241], v[96:99]
	v_mfma_f32_16x16x32_bf16 v[60:63], v[164:167], v[202:205], v[60:63]
	v_mfma_f32_16x16x32_bf16 v[56:59], v[172:175], v[202:205], v[56:59]
	v_mfma_f32_16x16x32_bf16 v[52:55], v[164:167], v[210:213], v[52:55]
	v_mfma_f32_16x16x32_bf16 v[48:51], v[172:175], v[210:213], v[48:51]
	v_mfma_f32_16x16x32_bf16 v[44:47], v[164:167], v[218:221], v[44:47]
	v_mfma_f32_16x16x32_bf16 v[40:43], v[172:175], v[218:221], v[40:43]
	v_mfma_f32_16x16x32_bf16 v[36:39], v[164:167], v[226:229], v[36:39]
	v_mfma_f32_16x16x32_bf16 v[32:35], v[172:175], v[226:229], v[32:35]
	v_mfma_f32_16x16x32_bf16 v[60:63], v[168:171], v[206:209], v[60:63]
	v_mfma_f32_16x16x32_bf16 v[56:59], v[198:201], v[206:209], v[56:59]
	v_mfma_f32_16x16x32_bf16 v[52:55], v[168:171], v[214:217], v[52:55]
	v_mfma_f32_16x16x32_bf16 v[48:51], v[198:201], v[214:217], v[48:51]
	v_mfma_f32_16x16x32_bf16 v[44:47], v[168:171], v[222:225], v[44:47]
	v_mfma_f32_16x16x32_bf16 v[40:43], v[198:201], v[222:225], v[40:43]
	v_mfma_f32_16x16x32_bf16 v[36:39], v[168:171], v[238:241], v[36:39]
	v_mfma_f32_16x16x32_bf16 v[32:35], v[198:201], v[238:241], v[32:35]
	s_setprio 0
	s_barrier
	s_add_i32 s30, s30, s5
	v_lshl_add_u64 v[138:139], s[46:47], 0, v[130:131]
	s_mov_b32 m0, s30
	ds_read_b128 v[202:205], v145 offset:16384
	ds_read_b128 v[206:209], v145 offset:17408
	ds_read_b128 v[210:213], v145 offset:18432
	ds_read_b128 v[214:217], v145 offset:19456
	ds_read_b128 v[218:221], v145 offset:20480
	ds_read_b128 v[222:225], v145 offset:21504
	ds_read_b128 v[226:229], v145 offset:22528
	ds_read_b128 v[238:241], v145 offset:23552
	global_load_lds_dwordx4 v[138:139], off
	s_add_i32 m0, s30, 0x2000
	s_add_u32 s30, s46, 0x40000
	v_lshl_add_u64 v[176:177], s[46:47], 0, v[132:133]
	s_addc_u32 s31, s47, 0
	s_add_i32 s38, s83, s5
	global_load_lds_dwordx4 v[176:177], off
	v_lshl_add_u64 v[242:243], s[30:31], 0, v[130:131]
	s_mov_b32 m0, s38
	v_lshl_add_u64 v[244:245], s[48:49], 0, v[132:133]
	global_load_lds_dwordx4 v[242:243], off
	v_lshl_add_u64 v[242:243], s[30:31], 0, v[132:133]
	s_add_i32 m0, s38, 0x2000
	s_nop 0
	global_load_lds_dwordx4 v[242:243], off
	v_lshl_add_u64 v[242:243], s[48:49], 0, v[130:131]
	s_mov_b32 m0, s40
	s_nop 0
	global_load_lds_dwordx4 v[242:243], off
	s_mov_b32 m0, s41
	s_nop 0
	global_load_lds_dwordx4 v[244:245], off
	s_waitcnt vmcnt(8) lgkmcnt(0)
	s_barrier
	s_setprio 1
	v_mfma_f32_16x16x32_bf16 v[92:95], v[148:151], v[202:205], v[92:95]
	v_mfma_f32_16x16x32_bf16 v[88:91], v[156:159], v[202:205], v[88:91]
	v_mfma_f32_16x16x32_bf16 v[84:87], v[148:151], v[210:213], v[84:87]
	v_mfma_f32_16x16x32_bf16 v[80:83], v[156:159], v[210:213], v[80:83]
	v_mfma_f32_16x16x32_bf16 v[76:79], v[148:151], v[218:221], v[76:79]
	v_mfma_f32_16x16x32_bf16 v[72:75], v[156:159], v[218:221], v[72:75]
	v_mfma_f32_16x16x32_bf16 v[68:71], v[148:151], v[226:229], v[68:71]
	v_mfma_f32_16x16x32_bf16 v[64:67], v[156:159], v[226:229], v[64:67]
	v_mfma_f32_16x16x32_bf16 v[92:95], v[152:155], v[206:209], v[92:95]
	v_mfma_f32_16x16x32_bf16 v[88:91], v[160:163], v[206:209], v[88:91]
	v_mfma_f32_16x16x32_bf16 v[84:87], v[152:155], v[214:217], v[84:87]
	v_mfma_f32_16x16x32_bf16 v[80:83], v[160:163], v[214:217], v[80:83]
	v_mfma_f32_16x16x32_bf16 v[76:79], v[152:155], v[222:225], v[76:79]
	v_mfma_f32_16x16x32_bf16 v[72:75], v[160:163], v[222:225], v[72:75]
	v_mfma_f32_16x16x32_bf16 v[68:71], v[152:155], v[238:241], v[68:71]
	v_mfma_f32_16x16x32_bf16 v[64:67], v[160:163], v[238:241], v[64:67]
	v_mfma_f32_16x16x32_bf16 v[28:31], v[164:167], v[202:205], v[28:31]
	v_mfma_f32_16x16x32_bf16 v[24:27], v[172:175], v[202:205], v[24:27]
	v_mfma_f32_16x16x32_bf16 v[20:23], v[164:167], v[210:213], v[20:23]
	v_mfma_f32_16x16x32_bf16 v[16:19], v[172:175], v[210:213], v[16:19]
	v_mfma_f32_16x16x32_bf16 v[12:15], v[164:167], v[218:221], v[12:15]
	v_mfma_f32_16x16x32_bf16 v[8:11], v[172:175], v[218:221], v[8:11]
	v_mfma_f32_16x16x32_bf16 v[4:7], v[164:167], v[226:229], v[4:7]
	v_mfma_f32_16x16x32_bf16 v[0:3], v[172:175], v[226:229], v[0:3]
	v_mfma_f32_16x16x32_bf16 v[28:31], v[168:171], v[206:209], v[28:31]
	v_mfma_f32_16x16x32_bf16 v[24:27], v[198:201], v[206:209], v[24:27]
	v_mfma_f32_16x16x32_bf16 v[20:23], v[168:171], v[214:217], v[20:23]
	v_mfma_f32_16x16x32_bf16 v[16:19], v[198:201], v[214:217], v[16:19]
	v_mfma_f32_16x16x32_bf16 v[12:15], v[168:171], v[222:225], v[12:15]
	v_mfma_f32_16x16x32_bf16 v[8:11], v[198:201], v[222:225], v[8:11]
	v_mfma_f32_16x16x32_bf16 v[4:7], v[168:171], v[238:241], v[4:7]
	v_mfma_f32_16x16x32_bf16 v[0:3], v[198:201], v[238:241], v[0:3]
	s_setprio 0
	s_barrier
	s_add_i32 s38, 0, 0x18000
	v_add_u32_e32 v147, s38, v141
	s_add_i32 s39, 0, 0x1c000
	ds_read_b128 v[148:151], v147
	ds_read_b128 v[152:155], v147 offset:1024
	ds_read_b128 v[156:159], v147 offset:2048
	ds_read_b128 v[160:163], v147 offset:3072
	v_add_u32_e32 v147, s39, v141
	ds_read_b128 v[164:167], v147
	ds_read_b128 v[168:171], v147 offset:1024
	ds_read_b128 v[172:175], v147 offset:2048
	ds_read_b128 v[198:201], v147 offset:3072
	s_add_u32 s30, s48, 0x40000
	s_addc_u32 s31, s49, 0
	s_mov_b32 m0, s42
	v_lshl_add_u64 v[246:247], s[30:31], 0, v[130:131]
	ds_read_b128 v[202:205], v145 offset:32768
	ds_read_b128 v[206:209], v145 offset:33792
	ds_read_b128 v[210:213], v145 offset:34816
	ds_read_b128 v[214:217], v145 offset:35840
	ds_read_b128 v[218:221], v145 offset:36864
	ds_read_b128 v[222:225], v145 offset:37888
	ds_read_b128 v[226:229], v145 offset:38912
	ds_read_b128 v[238:241], v145 offset:39936
	global_load_lds_dwordx4 v[246:247], off
	v_lshl_add_u64 v[246:247], s[30:31], 0, v[132:133]
	s_mov_b32 m0, s43
	s_nop 0
	global_load_lds_dwordx4 v[246:247], off
	s_waitcnt vmcnt(8) lgkmcnt(0)
	s_barrier
	s_setprio 1
	v_mfma_f32_16x16x32_bf16 v[124:127], v[148:151], v[202:205], v[124:127]
	v_mfma_f32_16x16x32_bf16 v[120:123], v[156:159], v[202:205], v[120:123]
	v_mfma_f32_16x16x32_bf16 v[116:119], v[148:151], v[210:213], v[116:119]
	v_mfma_f32_16x16x32_bf16 v[112:115], v[156:159], v[210:213], v[112:115]
	v_mfma_f32_16x16x32_bf16 v[108:111], v[148:151], v[218:221], v[108:111]
	v_mfma_f32_16x16x32_bf16 v[104:107], v[156:159], v[218:221], v[104:107]
	v_mfma_f32_16x16x32_bf16 v[100:103], v[148:151], v[226:229], v[100:103]
	v_mfma_f32_16x16x32_bf16 v[96:99], v[156:159], v[226:229], v[96:99]
	v_mfma_f32_16x16x32_bf16 v[124:127], v[152:155], v[206:209], v[124:127]
	v_mfma_f32_16x16x32_bf16 v[120:123], v[160:163], v[206:209], v[120:123]
	v_mfma_f32_16x16x32_bf16 v[116:119], v[152:155], v[214:217], v[116:119]
	v_mfma_f32_16x16x32_bf16 v[112:115], v[160:163], v[214:217], v[112:115]
	v_mfma_f32_16x16x32_bf16 v[108:111], v[152:155], v[222:225], v[108:111]
	v_mfma_f32_16x16x32_bf16 v[104:107], v[160:163], v[222:225], v[104:107]
	v_mfma_f32_16x16x32_bf16 v[100:103], v[152:155], v[238:241], v[100:103]
	v_mfma_f32_16x16x32_bf16 v[96:99], v[160:163], v[238:241], v[96:99]
	v_mfma_f32_16x16x32_bf16 v[60:63], v[164:167], v[202:205], v[60:63]
	v_mfma_f32_16x16x32_bf16 v[56:59], v[172:175], v[202:205], v[56:59]
	v_mfma_f32_16x16x32_bf16 v[52:55], v[164:167], v[210:213], v[52:55]
	v_mfma_f32_16x16x32_bf16 v[48:51], v[172:175], v[210:213], v[48:51]
	v_mfma_f32_16x16x32_bf16 v[44:47], v[164:167], v[218:221], v[44:47]
	v_mfma_f32_16x16x32_bf16 v[40:43], v[172:175], v[218:221], v[40:43]
	v_mfma_f32_16x16x32_bf16 v[36:39], v[164:167], v[226:229], v[36:39]
	v_mfma_f32_16x16x32_bf16 v[32:35], v[172:175], v[226:229], v[32:35]
	v_mfma_f32_16x16x32_bf16 v[60:63], v[168:171], v[206:209], v[60:63]
	v_mfma_f32_16x16x32_bf16 v[56:59], v[198:201], v[206:209], v[56:59]
	v_mfma_f32_16x16x32_bf16 v[52:55], v[168:171], v[214:217], v[52:55]
	v_mfma_f32_16x16x32_bf16 v[48:51], v[198:201], v[214:217], v[48:51]
	v_mfma_f32_16x16x32_bf16 v[44:47], v[168:171], v[222:225], v[44:47]
	v_mfma_f32_16x16x32_bf16 v[40:43], v[198:201], v[222:225], v[40:43]
	v_mfma_f32_16x16x32_bf16 v[36:39], v[168:171], v[238:241], v[36:39]
	v_mfma_f32_16x16x32_bf16 v[32:35], v[198:201], v[238:241], v[32:35]
	s_setprio 0
	s_barrier
	s_add_i32 s30, s38, s5
	v_lshl_add_u64 v[138:139], v[138:139], 0, s[90:91]
	s_mov_b32 m0, s30
	ds_read_b128 v[202:205], v145 offset:49152
	ds_read_b128 v[206:209], v145 offset:50176
	ds_read_b128 v[210:213], v145 offset:51200
	ds_read_b128 v[214:217], v145 offset:52224
	ds_read_b128 v[218:221], v145 offset:53248
	ds_read_b128 v[222:225], v145 offset:54272
	ds_read_b128 v[226:229], v145 offset:55296
	ds_read_b128 v[238:241], v145 offset:56320
	global_load_lds_dwordx4 v[138:139], off
	s_add_i32 m0, s30, 0x2000
	s_add_u32 s30, s46, 0x40080
	v_lshl_add_u64 v[138:139], v[176:177], 0, s[90:91]
	s_addc_u32 s31, s47, 0
	s_add_i32 s38, s39, s5
	global_load_lds_dwordx4 v[138:139], off
	v_lshl_add_u64 v[138:139], s[30:31], 0, v[130:131]
	s_mov_b32 m0, s38
	s_nop 0
	global_load_lds_dwordx4 v[138:139], off
	v_lshl_add_u64 v[138:139], s[30:31], 0, v[132:133]
	s_add_i32 m0, s38, 0x2000
	s_nop 0
	global_load_lds_dwordx4 v[138:139], off
	v_lshl_add_u64 v[138:139], v[242:243], 0, s[90:91]
	s_mov_b32 m0, s55
	s_nop 0
	global_load_lds_dwordx4 v[138:139], off
	v_lshl_add_u64 v[138:139], v[244:245], 0, s[90:91]
	s_mov_b32 m0, s56
	s_nop 0
	global_load_lds_dwordx4 v[138:139], off
	s_waitcnt vmcnt(8) lgkmcnt(0)
	s_barrier
	s_setprio 1
	v_mfma_f32_16x16x32_bf16 v[92:95], v[148:151], v[202:205], v[92:95]
	v_mfma_f32_16x16x32_bf16 v[88:91], v[156:159], v[202:205], v[88:91]
	v_mfma_f32_16x16x32_bf16 v[84:87], v[148:151], v[210:213], v[84:87]
	v_mfma_f32_16x16x32_bf16 v[80:83], v[156:159], v[210:213], v[80:83]
	v_mfma_f32_16x16x32_bf16 v[76:79], v[148:151], v[218:221], v[76:79]
	v_mfma_f32_16x16x32_bf16 v[72:75], v[156:159], v[218:221], v[72:75]
	v_mfma_f32_16x16x32_bf16 v[68:71], v[148:151], v[226:229], v[68:71]
	v_mfma_f32_16x16x32_bf16 v[64:67], v[156:159], v[226:229], v[64:67]
	v_mfma_f32_16x16x32_bf16 v[92:95], v[152:155], v[206:209], v[92:95]
	v_mfma_f32_16x16x32_bf16 v[88:91], v[160:163], v[206:209], v[88:91]
	v_mfma_f32_16x16x32_bf16 v[84:87], v[152:155], v[214:217], v[84:87]
	v_mfma_f32_16x16x32_bf16 v[80:83], v[160:163], v[214:217], v[80:83]
	v_mfma_f32_16x16x32_bf16 v[76:79], v[152:155], v[222:225], v[76:79]
	v_mfma_f32_16x16x32_bf16 v[72:75], v[160:163], v[222:225], v[72:75]
	v_mfma_f32_16x16x32_bf16 v[68:71], v[152:155], v[238:241], v[68:71]
	v_mfma_f32_16x16x32_bf16 v[64:67], v[160:163], v[238:241], v[64:67]
	v_mfma_f32_16x16x32_bf16 v[28:31], v[164:167], v[202:205], v[28:31]
	v_mfma_f32_16x16x32_bf16 v[24:27], v[172:175], v[202:205], v[24:27]
	v_mfma_f32_16x16x32_bf16 v[20:23], v[164:167], v[210:213], v[20:23]
	v_mfma_f32_16x16x32_bf16 v[16:19], v[172:175], v[210:213], v[16:19]
	v_mfma_f32_16x16x32_bf16 v[12:15], v[164:167], v[218:221], v[12:15]
	v_mfma_f32_16x16x32_bf16 v[8:11], v[172:175], v[218:221], v[8:11]
	v_mfma_f32_16x16x32_bf16 v[4:7], v[164:167], v[226:229], v[4:7]
	v_mfma_f32_16x16x32_bf16 v[0:3], v[172:175], v[226:229], v[0:3]
	v_mfma_f32_16x16x32_bf16 v[28:31], v[168:171], v[206:209], v[28:31]
	v_mfma_f32_16x16x32_bf16 v[24:27], v[198:201], v[206:209], v[24:27]
	v_mfma_f32_16x16x32_bf16 v[20:23], v[168:171], v[214:217], v[20:23]
	v_mfma_f32_16x16x32_bf16 v[16:19], v[198:201], v[214:217], v[16:19]
	v_mfma_f32_16x16x32_bf16 v[12:15], v[168:171], v[222:225], v[12:15]
	v_mfma_f32_16x16x32_bf16 v[8:11], v[198:201], v[222:225], v[8:11]
	v_mfma_f32_16x16x32_bf16 v[4:7], v[168:171], v[238:241], v[4:7]
	v_mfma_f32_16x16x32_bf16 v[0:3], v[198:201], v[238:241], v[0:3]
	s_setprio 0
	s_barrier
	s_add_i32 s73, s73, 2
	s_add_u32 s27, s27, 0x100
	s_addc_u32 s29, s29, 0
	s_cmp_gt_u32 s73, 13
	s_mov_b64 s[38:39], s[44:45]
	s_cbranch_scc0 .LBB0_224
	s_and_b64 vcc, exec, s[24:25]
	s_cbranch_vccz .LBB0_227
	s_barrier

.LBB0_273:
	s_add_u32 s30, s28, 0xfffc0080
	s_addc_u32 s31, s29, -1
	s_add_i32 s59, 0, 0x10000
	s_cmp_eq_u32 s58, 12
	s_cselect_b32 s45, s27, s31
	s_cselect_b32 s44, s53, s30
	v_add_u32_e32 v142, s59, v145
	s_cselect_b32 s35, s25, s57
	s_cselect_b32 s34, s55, s56
	s_add_i32 s60, 0, 0x14000
	ds_read_b128 v[146:149], v142
	ds_read_b128 v[150:153], v142 offset:1024
	ds_read_b128 v[154:157], v142 offset:2048
	ds_read_b128 v[158:161], v142 offset:3072
	v_add_u32_e32 v142, s60, v145
	ds_read_b128 v[162:165], v142
	ds_read_b128 v[166:169], v142 offset:1024
	ds_read_b128 v[170:173], v142 offset:2048
	ds_read_b128 v[174:177], v142 offset:3072
	v_lshl_add_u64 v[142:143], s[28:29], 0, v[138:139]
	s_add_i32 m0, s19, 0xc000
	ds_read_b128 v[198:201], v141
	ds_read_b128 v[202:205], v141 offset:1024
	ds_read_b128 v[206:209], v141 offset:2048
	ds_read_b128 v[210:213], v141 offset:3072
	ds_read_b128 v[214:217], v141 offset:4096
	ds_read_b128 v[218:221], v141 offset:5120
	ds_read_b128 v[222:225], v141 offset:6144
	ds_read_b128 v[226:229], v141 offset:7168
	global_load_lds_dwordx4 v[142:143], off
	v_lshl_add_u64 v[142:143], s[28:29], 0, v[136:137]
	s_add_i32 m0, s19, 0xe000
	s_nop 0
	global_load_lds_dwordx4 v[142:143], off
	s_waitcnt vmcnt(8) lgkmcnt(0)
	s_barrier
	s_setprio 1
	v_mfma_f32_16x16x32_bf16 v[108:111], v[146:149], v[198:201], v[108:111]
	v_mfma_f32_16x16x32_bf16 v[116:119], v[154:157], v[198:201], v[116:119]
	v_mfma_f32_16x16x32_bf16 v[92:95], v[146:149], v[206:209], v[92:95]
	v_mfma_f32_16x16x32_bf16 v[100:103], v[154:157], v[206:209], v[100:103]
	v_mfma_f32_16x16x32_bf16 v[68:71], v[146:149], v[214:217], v[68:71]
	v_mfma_f32_16x16x32_bf16 v[76:79], v[154:157], v[214:217], v[76:79]
	v_mfma_f32_16x16x32_bf16 v[40:43], v[146:149], v[222:225], v[40:43]
	v_mfma_f32_16x16x32_bf16 v[44:47], v[154:157], v[222:225], v[44:47]
	v_mfma_f32_16x16x32_bf16 v[108:111], v[150:153], v[202:205], v[108:111]
	v_mfma_f32_16x16x32_bf16 v[116:119], v[158:161], v[202:205], v[116:119]
	v_mfma_f32_16x16x32_bf16 v[92:95], v[150:153], v[210:213], v[92:95]
	v_mfma_f32_16x16x32_bf16 v[100:103], v[158:161], v[210:213], v[100:103]
	v_mfma_f32_16x16x32_bf16 v[68:71], v[150:153], v[218:221], v[68:71]
	v_mfma_f32_16x16x32_bf16 v[76:79], v[158:161], v[218:221], v[76:79]
	v_mfma_f32_16x16x32_bf16 v[40:43], v[150:153], v[226:229], v[40:43]
	v_mfma_f32_16x16x32_bf16 v[44:47], v[158:161], v[226:229], v[44:47]
	v_mfma_f32_16x16x32_bf16 v[120:123], v[162:165], v[198:201], v[120:123]
	v_mfma_f32_16x16x32_bf16 v[124:127], v[170:173], v[198:201], v[124:127]
	v_mfma_f32_16x16x32_bf16 v[104:107], v[162:165], v[206:209], v[104:107]
	v_mfma_f32_16x16x32_bf16 v[112:115], v[170:173], v[206:209], v[112:115]
	v_mfma_f32_16x16x32_bf16 v[88:91], v[162:165], v[214:217], v[88:91]
	v_mfma_f32_16x16x32_bf16 v[96:99], v[170:173], v[214:217], v[96:99]
	v_mfma_f32_16x16x32_bf16 v[64:67], v[162:165], v[222:225], v[64:67]
	v_mfma_f32_16x16x32_bf16 v[72:75], v[170:173], v[222:225], v[72:75]
	v_mfma_f32_16x16x32_bf16 v[120:123], v[166:169], v[202:205], v[120:123]
	v_mfma_f32_16x16x32_bf16 v[124:127], v[174:177], v[202:205], v[124:127]
	v_mfma_f32_16x16x32_bf16 v[104:107], v[166:169], v[210:213], v[104:107]
	v_mfma_f32_16x16x32_bf16 v[112:115], v[174:177], v[210:213], v[112:115]
	v_mfma_f32_16x16x32_bf16 v[88:91], v[166:169], v[218:221], v[88:91]
	v_mfma_f32_16x16x32_bf16 v[96:99], v[174:177], v[218:221], v[96:99]
	v_mfma_f32_16x16x32_bf16 v[64:67], v[166:169], v[226:229], v[64:67]
	v_mfma_f32_16x16x32_bf16 v[72:75], v[174:177], v[226:229], v[72:75]
	s_setprio 0
	s_barrier
	s_add_i32 s30, s59, s4
	v_lshl_add_u64 v[142:143], s[34:35], 0, v[128:129]
	s_mov_b32 m0, s30
	ds_read_b128 v[198:201], v141 offset:16384
	ds_read_b128 v[202:205], v141 offset:17408
	ds_read_b128 v[206:209], v141 offset:18432
	ds_read_b128 v[210:213], v141 offset:19456
	ds_read_b128 v[214:217], v141 offset:20480
	ds_read_b128 v[218:221], v141 offset:21504
	ds_read_b128 v[222:225], v141 offset:22528
	ds_read_b128 v[226:229], v141 offset:23552
	global_load_lds_dwordx4 v[142:143], off
	s_add_i32 m0, s30, 0x2000
	s_add_u32 s30, s34, 0x40000
	v_lshl_add_u64 v[238:239], s[34:35], 0, v[130:131]
	s_addc_u32 s31, s35, 0
	s_add_i32 s59, s60, s4
	global_load_lds_dwordx4 v[238:239], off
	v_lshl_add_u64 v[240:241], s[30:31], 0, v[128:129]
	s_mov_b32 m0, s59
	v_lshl_add_u64 v[242:243], s[44:45], 0, v[132:133]
	global_load_lds_dwordx4 v[240:241], off
	v_lshl_add_u64 v[240:241], s[30:31], 0, v[130:131]
	s_add_i32 m0, s59, 0x2000
	s_nop 0
	global_load_lds_dwordx4 v[240:241], off
	v_lshl_add_u64 v[240:241], s[44:45], 0, v[134:135]
	s_mov_b32 m0, s19
	s_nop 0
	global_load_lds_dwordx4 v[240:241], off
	s_mov_b32 m0, s43
	s_nop 0
	global_load_lds_dwordx4 v[242:243], off
	s_waitcnt vmcnt(8) lgkmcnt(0)
	s_barrier
	s_setprio 1
	v_mfma_f32_16x16x32_bf16 v[52:55], v[146:149], v[198:201], v[52:55]
	v_mfma_f32_16x16x32_bf16 v[60:63], v[154:157], v[198:201], v[60:63]
	v_mfma_f32_16x16x32_bf16 v[28:31], v[146:149], v[206:209], v[28:31]
	v_mfma_f32_16x16x32_bf16 v[36:39], v[154:157], v[206:209], v[36:39]
	v_mfma_f32_16x16x32_bf16 v[12:15], v[146:149], v[214:217], v[12:15]
	v_mfma_f32_16x16x32_bf16 v[16:19], v[154:157], v[214:217], v[16:19]
	v_mfma_f32_16x16x32_bf16 v[0:3], v[146:149], v[222:225], v[0:3]
	v_mfma_f32_16x16x32_bf16 v[4:7], v[154:157], v[222:225], v[4:7]
	v_mfma_f32_16x16x32_bf16 v[52:55], v[150:153], v[202:205], v[52:55]
	v_mfma_f32_16x16x32_bf16 v[60:63], v[158:161], v[202:205], v[60:63]
	v_mfma_f32_16x16x32_bf16 v[28:31], v[150:153], v[210:213], v[28:31]
	v_mfma_f32_16x16x32_bf16 v[36:39], v[158:161], v[210:213], v[36:39]
	v_mfma_f32_16x16x32_bf16 v[12:15], v[150:153], v[218:221], v[12:15]
	v_mfma_f32_16x16x32_bf16 v[16:19], v[158:161], v[218:221], v[16:19]
	v_mfma_f32_16x16x32_bf16 v[0:3], v[150:153], v[226:229], v[0:3]
	v_mfma_f32_16x16x32_bf16 v[4:7], v[158:161], v[226:229], v[4:7]
	v_mfma_f32_16x16x32_bf16 v[80:83], v[162:165], v[198:201], v[80:83]
	v_mfma_f32_16x16x32_bf16 v[84:87], v[170:173], v[198:201], v[84:87]
	v_mfma_f32_16x16x32_bf16 v[48:51], v[162:165], v[206:209], v[48:51]
	v_mfma_f32_16x16x32_bf16 v[56:59], v[170:173], v[206:209], v[56:59]
	v_mfma_f32_16x16x32_bf16 v[24:27], v[162:165], v[214:217], v[24:27]
	v_mfma_f32_16x16x32_bf16 v[32:35], v[170:173], v[214:217], v[32:35]
	v_mfma_f32_16x16x32_bf16 v[8:11], v[162:165], v[222:225], v[8:11]
	v_mfma_f32_16x16x32_bf16 v[20:23], v[170:173], v[222:225], v[20:23]
	v_mfma_f32_16x16x32_bf16 v[80:83], v[166:169], v[202:205], v[80:83]
	v_mfma_f32_16x16x32_bf16 v[84:87], v[174:177], v[202:205], v[84:87]
	v_mfma_f32_16x16x32_bf16 v[48:51], v[166:169], v[210:213], v[48:51]
	v_mfma_f32_16x16x32_bf16 v[56:59], v[174:177], v[210:213], v[56:59]
	v_mfma_f32_16x16x32_bf16 v[24:27], v[166:169], v[218:221], v[24:27]
	v_mfma_f32_16x16x32_bf16 v[32:35], v[174:177], v[218:221], v[32:35]
	v_mfma_f32_16x16x32_bf16 v[8:11], v[166:169], v[226:229], v[8:11]
	v_mfma_f32_16x16x32_bf16 v[20:23], v[174:177], v[226:229], v[20:23]
	s_setprio 0
	s_barrier
	s_add_i32 s59, 0, 0x18000
	s_add_i32 s60, 0, 0x1c000
	v_add_u32_e32 v158, s59, v145
	v_add_u32_e32 v174, s60, v145
	ds_read_b128 v[146:149], v158
	ds_read_b128 v[150:153], v158 offset:1024
	ds_read_b128 v[154:157], v158 offset:2048
	ds_read_b128 v[158:161], v158 offset:3072
	ds_read_b128 v[162:165], v174
	ds_read_b128 v[166:169], v174 offset:1024
	ds_read_b128 v[170:173], v174 offset:2048
	ds_read_b128 v[174:177], v174 offset:3072
	s_add_u32 s30, s44, 0x40000
	s_addc_u32 s31, s45, 0
	s_mov_b32 m0, s46
	v_lshl_add_u64 v[244:245], s[30:31], 0, v[134:135]
	ds_read_b128 v[198:201], v141 offset:32768
	ds_read_b128 v[202:205], v141 offset:33792
	ds_read_b128 v[206:209], v141 offset:34816
	ds_read_b128 v[210:213], v141 offset:35840
	ds_read_b128 v[214:217], v141 offset:36864
	ds_read_b128 v[218:221], v141 offset:37888
	ds_read_b128 v[222:225], v141 offset:38912
	ds_read_b128 v[226:229], v141 offset:39936
	global_load_lds_dwordx4 v[244:245], off
	v_lshl_add_u64 v[244:245], s[30:31], 0, v[132:133]
	s_mov_b32 m0, s47
	s_nop 0
	global_load_lds_dwordx4 v[244:245], off
	s_waitcnt vmcnt(8) lgkmcnt(0)
	s_barrier
	s_setprio 1
	v_mfma_f32_16x16x32_bf16 v[108:111], v[146:149], v[198:201], v[108:111]
	v_mfma_f32_16x16x32_bf16 v[116:119], v[154:157], v[198:201], v[116:119]
	v_mfma_f32_16x16x32_bf16 v[92:95], v[146:149], v[206:209], v[92:95]
	v_mfma_f32_16x16x32_bf16 v[100:103], v[154:157], v[206:209], v[100:103]
	v_mfma_f32_16x16x32_bf16 v[68:71], v[146:149], v[214:217], v[68:71]
	v_mfma_f32_16x16x32_bf16 v[76:79], v[154:157], v[214:217], v[76:79]
	v_mfma_f32_16x16x32_bf16 v[40:43], v[146:149], v[222:225], v[40:43]
	v_mfma_f32_16x16x32_bf16 v[44:47], v[154:157], v[222:225], v[44:47]
	v_mfma_f32_16x16x32_bf16 v[108:111], v[150:153], v[202:205], v[108:111]
	v_mfma_f32_16x16x32_bf16 v[116:119], v[158:161], v[202:205], v[116:119]
	v_mfma_f32_16x16x32_bf16 v[92:95], v[150:153], v[210:213], v[92:95]
	v_mfma_f32_16x16x32_bf16 v[100:103], v[158:161], v[210:213], v[100:103]
	v_mfma_f32_16x16x32_bf16 v[68:71], v[150:153], v[218:221], v[68:71]
	v_mfma_f32_16x16x32_bf16 v[76:79], v[158:161], v[218:221], v[76:79]
	v_mfma_f32_16x16x32_bf16 v[40:43], v[150:153], v[226:229], v[40:43]
	v_mfma_f32_16x16x32_bf16 v[44:47], v[158:161], v[226:229], v[44:47]
	v_mfma_f32_16x16x32_bf16 v[120:123], v[162:165], v[198:201], v[120:123]
	v_mfma_f32_16x16x32_bf16 v[124:127], v[170:173], v[198:201], v[124:127]
	v_mfma_f32_16x16x32_bf16 v[104:107], v[162:165], v[206:209], v[104:107]
	v_mfma_f32_16x16x32_bf16 v[112:115], v[170:173], v[206:209], v[112:115]
	v_mfma_f32_16x16x32_bf16 v[88:91], v[162:165], v[214:217], v[88:91]
	v_mfma_f32_16x16x32_bf16 v[96:99], v[170:173], v[214:217], v[96:99]
	v_mfma_f32_16x16x32_bf16 v[64:67], v[162:165], v[222:225], v[64:67]
	v_mfma_f32_16x16x32_bf16 v[72:75], v[170:173], v[222:225], v[72:75]
	v_mfma_f32_16x16x32_bf16 v[120:123], v[166:169], v[202:205], v[120:123]
	v_mfma_f32_16x16x32_bf16 v[124:127], v[174:177], v[202:205], v[124:127]
	v_mfma_f32_16x16x32_bf16 v[104:107], v[166:169], v[210:213], v[104:107]
	v_mfma_f32_16x16x32_bf16 v[112:115], v[174:177], v[210:213], v[112:115]
	v_mfma_f32_16x16x32_bf16 v[88:91], v[166:169], v[218:221], v[88:91]
	v_mfma_f32_16x16x32_bf16 v[96:99], v[174:177], v[218:221], v[96:99]
	v_mfma_f32_16x16x32_bf16 v[64:67], v[166:169], v[226:229], v[64:67]
	v_mfma_f32_16x16x32_bf16 v[72:75], v[174:177], v[226:229], v[72:75]
	s_setprio 0
	s_barrier
	s_add_i32 s30, s59, s4
	v_lshl_add_u64 v[142:143], v[142:143], 0, s[90:91]
	s_mov_b32 m0, s30
	ds_read_b128 v[198:201], v141 offset:49152
	ds_read_b128 v[202:205], v141 offset:50176
	ds_read_b128 v[206:209], v141 offset:51200
	ds_read_b128 v[210:213], v141 offset:52224
	ds_read_b128 v[214:217], v141 offset:53248
	ds_read_b128 v[218:221], v141 offset:54272
	ds_read_b128 v[222:225], v141 offset:55296
	ds_read_b128 v[226:229], v141 offset:56320
	global_load_lds_dwordx4 v[142:143], off
	s_add_i32 m0, s30, 0x2000
	s_add_u32 s30, s34, 0x40080
	v_lshl_add_u64 v[142:143], v[238:239], 0, s[90:91]
	s_addc_u32 s31, s35, 0
	s_add_i32 s34, s60, s4
	global_load_lds_dwordx4 v[142:143], off
	v_lshl_add_u64 v[142:143], s[30:31], 0, v[128:129]
	s_mov_b32 m0, s34
	s_nop 0
	global_load_lds_dwordx4 v[142:143], off
	v_lshl_add_u64 v[142:143], s[30:31], 0, v[130:131]
	s_add_i32 m0, s34, 0x2000
	s_nop 0
	global_load_lds_dwordx4 v[142:143], off
	v_lshl_add_u64 v[142:143], v[240:241], 0, s[90:91]
	s_mov_b32 m0, s21
	s_nop 0
	global_load_lds_dwordx4 v[142:143], off
	v_lshl_add_u64 v[142:143], v[242:243], 0, s[90:91]
	s_mov_b32 m0, s48
	s_nop 0
	global_load_lds_dwordx4 v[142:143], off
	s_waitcnt vmcnt(8) lgkmcnt(0)
	s_barrier
	s_setprio 1
	v_mfma_f32_16x16x32_bf16 v[52:55], v[146:149], v[198:201], v[52:55]
	v_mfma_f32_16x16x32_bf16 v[60:63], v[154:157], v[198:201], v[60:63]
	v_mfma_f32_16x16x32_bf16 v[28:31], v[146:149], v[206:209], v[28:31]
	v_mfma_f32_16x16x32_bf16 v[36:39], v[154:157], v[206:209], v[36:39]
	v_mfma_f32_16x16x32_bf16 v[12:15], v[146:149], v[214:217], v[12:15]
	v_mfma_f32_16x16x32_bf16 v[16:19], v[154:157], v[214:217], v[16:19]
	v_mfma_f32_16x16x32_bf16 v[0:3], v[146:149], v[222:225], v[0:3]
	v_mfma_f32_16x16x32_bf16 v[4:7], v[154:157], v[222:225], v[4:7]
	v_mfma_f32_16x16x32_bf16 v[52:55], v[150:153], v[202:205], v[52:55]
	v_mfma_f32_16x16x32_bf16 v[60:63], v[158:161], v[202:205], v[60:63]
	v_mfma_f32_16x16x32_bf16 v[28:31], v[150:153], v[210:213], v[28:31]
	v_mfma_f32_16x16x32_bf16 v[36:39], v[158:161], v[210:213], v[36:39]
	v_mfma_f32_16x16x32_bf16 v[12:15], v[150:153], v[218:221], v[12:15]
	v_mfma_f32_16x16x32_bf16 v[16:19], v[158:161], v[218:221], v[16:19]
	v_mfma_f32_16x16x32_bf16 v[0:3], v[150:153], v[226:229], v[0:3]
	v_mfma_f32_16x16x32_bf16 v[4:7], v[158:161], v[226:229], v[4:7]
	v_mfma_f32_16x16x32_bf16 v[80:83], v[162:165], v[198:201], v[80:83]
	v_mfma_f32_16x16x32_bf16 v[84:87], v[170:173], v[198:201], v[84:87]
	v_mfma_f32_16x16x32_bf16 v[48:51], v[162:165], v[206:209], v[48:51]
	v_mfma_f32_16x16x32_bf16 v[56:59], v[170:173], v[206:209], v[56:59]
	v_mfma_f32_16x16x32_bf16 v[24:27], v[162:165], v[214:217], v[24:27]
	v_mfma_f32_16x16x32_bf16 v[32:35], v[170:173], v[214:217], v[32:35]
	v_mfma_f32_16x16x32_bf16 v[8:11], v[162:165], v[222:225], v[8:11]
	v_mfma_f32_16x16x32_bf16 v[20:23], v[170:173], v[222:225], v[20:23]
	v_mfma_f32_16x16x32_bf16 v[80:83], v[166:169], v[202:205], v[80:83]
	v_mfma_f32_16x16x32_bf16 v[84:87], v[174:177], v[202:205], v[84:87]
	v_mfma_f32_16x16x32_bf16 v[48:51], v[166:169], v[210:213], v[48:51]
	v_mfma_f32_16x16x32_bf16 v[56:59], v[174:177], v[210:213], v[56:59]
	v_mfma_f32_16x16x32_bf16 v[24:27], v[166:169], v[218:221], v[24:27]
	v_mfma_f32_16x16x32_bf16 v[32:35], v[174:177], v[218:221], v[32:35]
	v_mfma_f32_16x16x32_bf16 v[8:11], v[166:169], v[226:229], v[8:11]
	v_mfma_f32_16x16x32_bf16 v[20:23], v[174:177], v[226:229], v[20:23]
	s_setprio 0
	s_barrier
	s_add_i32 s58, s58, 2
	s_add_u32 s56, s56, 0x100
	s_addc_u32 s57, s57, 0
	s_add_u32 s28, s28, 0x100
	s_addc_u32 s29, s29, 0
	s_cmp_gt_u32 s58, 13
	s_cbranch_scc0 .LBB0_273
	s_and_b64 vcc, exec, s[16:17]
	s_cbranch_vccz .LBB0_276
	s_barrier

.LBB0_296:
	s_add_u32 s8, s10, 0x100
	s_addc_u32 s9, s11, 0
	s_add_i32 s30, 0, 0x10000
	s_cmp_eq_u32 s55, 2
	s_cselect_b32 s37, s27, s9
	s_cselect_b32 s36, s26, s8
	v_add_u32_e32 v138, s30, v141
	s_cselect_b32 s35, s29, s53
	s_cselect_b32 s34, s28, s52
	s_add_i32 s31, 0, 0x14000
	ds_read_b128 v[148:151], v138
	ds_read_b128 v[152:155], v138 offset:1024
	ds_read_b128 v[156:159], v138 offset:2048
	ds_read_b128 v[160:163], v138 offset:3072
	v_add_u32_e32 v138, s31, v141
	ds_read_b128 v[164:167], v138
	ds_read_b128 v[168:171], v138 offset:1024
	ds_read_b128 v[172:175], v138 offset:2048
	ds_read_b128 v[198:201], v138 offset:3072
	v_lshl_add_u64 v[138:139], s[10:11], 0, v[136:137]
	s_add_i32 m0, s39, 0xc000
	ds_read_b128 v[202:205], v145
	ds_read_b128 v[206:209], v145 offset:1024
	ds_read_b128 v[210:213], v145 offset:2048
	ds_read_b128 v[214:217], v145 offset:3072
	ds_read_b128 v[218:221], v145 offset:4096
	ds_read_b128 v[222:225], v145 offset:5120
	ds_read_b128 v[226:229], v145 offset:6144
	ds_read_b128 v[238:241], v145 offset:7168
	global_load_lds_dwordx4 v[138:139], off
	v_lshl_add_u64 v[138:139], s[10:11], 0, v[134:135]
	s_add_i32 m0, s39, 0xe000
	s_nop 0
	global_load_lds_dwordx4 v[138:139], off
	s_waitcnt vmcnt(8) lgkmcnt(0)
	s_barrier
	s_setprio 1
	v_mfma_f32_16x16x32_bf16 v[124:127], v[148:151], v[202:205], v[124:127]
	v_mfma_f32_16x16x32_bf16 v[120:123], v[156:159], v[202:205], v[120:123]
	v_mfma_f32_16x16x32_bf16 v[116:119], v[148:151], v[210:213], v[116:119]
	v_mfma_f32_16x16x32_bf16 v[112:115], v[156:159], v[210:213], v[112:115]
	v_mfma_f32_16x16x32_bf16 v[108:111], v[148:151], v[218:221], v[108:111]
	v_mfma_f32_16x16x32_bf16 v[104:107], v[156:159], v[218:221], v[104:107]
	v_mfma_f32_16x16x32_bf16 v[100:103], v[148:151], v[226:229], v[100:103]
	v_mfma_f32_16x16x32_bf16 v[96:99], v[156:159], v[226:229], v[96:99]
	v_mfma_f32_16x16x32_bf16 v[124:127], v[152:155], v[206:209], v[124:127]
	v_mfma_f32_16x16x32_bf16 v[120:123], v[160:163], v[206:209], v[120:123]
	v_mfma_f32_16x16x32_bf16 v[116:119], v[152:155], v[214:217], v[116:119]
	v_mfma_f32_16x16x32_bf16 v[112:115], v[160:163], v[214:217], v[112:115]
	v_mfma_f32_16x16x32_bf16 v[108:111], v[152:155], v[222:225], v[108:111]
	v_mfma_f32_16x16x32_bf16 v[104:107], v[160:163], v[222:225], v[104:107]
	v_mfma_f32_16x16x32_bf16 v[100:103], v[152:155], v[238:241], v[100:103]
	v_mfma_f32_16x16x32_bf16 v[96:99], v[160:163], v[238:241], v[96:99]
	v_mfma_f32_16x16x32_bf16 v[60:63], v[164:167], v[202:205], v[60:63]
	v_mfma_f32_16x16x32_bf16 v[56:59], v[172:175], v[202:205], v[56:59]
	v_mfma_f32_16x16x32_bf16 v[52:55], v[164:167], v[210:213], v[52:55]
	v_mfma_f32_16x16x32_bf16 v[48:51], v[172:175], v[210:213], v[48:51]
	v_mfma_f32_16x16x32_bf16 v[44:47], v[164:167], v[218:221], v[44:47]
	v_mfma_f32_16x16x32_bf16 v[40:43], v[172:175], v[218:221], v[40:43]
	v_mfma_f32_16x16x32_bf16 v[36:39], v[164:167], v[226:229], v[36:39]
	v_mfma_f32_16x16x32_bf16 v[32:35], v[172:175], v[226:229], v[32:35]
	v_mfma_f32_16x16x32_bf16 v[60:63], v[168:171], v[206:209], v[60:63]
	v_mfma_f32_16x16x32_bf16 v[56:59], v[198:201], v[206:209], v[56:59]
	v_mfma_f32_16x16x32_bf16 v[52:55], v[168:171], v[214:217], v[52:55]
	v_mfma_f32_16x16x32_bf16 v[48:51], v[198:201], v[214:217], v[48:51]
	v_mfma_f32_16x16x32_bf16 v[44:47], v[168:171], v[222:225], v[44:47]
	v_mfma_f32_16x16x32_bf16 v[40:43], v[198:201], v[222:225], v[40:43]
	v_mfma_f32_16x16x32_bf16 v[36:39], v[168:171], v[238:241], v[36:39]
	v_mfma_f32_16x16x32_bf16 v[32:35], v[198:201], v[238:241], v[32:35]
	s_setprio 0
	s_barrier
	s_add_i32 s10, s30, s38
	v_lshl_add_u64 v[138:139], s[34:35], 0, v[130:131]
	s_mov_b32 m0, s10
	ds_read_b128 v[202:205], v145 offset:16384
	ds_read_b128 v[206:209], v145 offset:17408
	ds_read_b128 v[210:213], v145 offset:18432
	ds_read_b128 v[214:217], v145 offset:19456
	ds_read_b128 v[218:221], v145 offset:20480
	ds_read_b128 v[222:225], v145 offset:21504
	ds_read_b128 v[226:229], v145 offset:22528
	ds_read_b128 v[238:241], v145 offset:23552
	global_load_lds_dwordx4 v[138:139], off
	s_add_i32 m0, s10, 0x2000
	s_add_u32 s10, s34, 0x18000
	v_lshl_add_u64 v[176:177], s[34:35], 0, v[132:133]
	s_addc_u32 s11, s35, 0
	s_add_i32 s30, s31, s38
	global_load_lds_dwordx4 v[176:177], off
	v_lshl_add_u64 v[242:243], s[10:11], 0, v[130:131]
	s_mov_b32 m0, s30
	v_lshl_add_u64 v[244:245], s[36:37], 0, v[132:133]
	global_load_lds_dwordx4 v[242:243], off
	v_lshl_add_u64 v[242:243], s[10:11], 0, v[132:133]
	s_add_i32 m0, s30, 0x2000
	s_nop 0
	global_load_lds_dwordx4 v[242:243], off
	v_lshl_add_u64 v[242:243], s[36:37], 0, v[130:131]
	s_mov_b32 m0, s39
	s_nop 0
	global_load_lds_dwordx4 v[242:243], off
	s_mov_b32 m0, s40
	s_nop 0
	global_load_lds_dwordx4 v[244:245], off
	s_waitcnt vmcnt(8) lgkmcnt(0)
	s_barrier
	s_setprio 1
	v_mfma_f32_16x16x32_bf16 v[92:95], v[148:151], v[202:205], v[92:95]
	v_mfma_f32_16x16x32_bf16 v[88:91], v[156:159], v[202:205], v[88:91]
	v_mfma_f32_16x16x32_bf16 v[84:87], v[148:151], v[210:213], v[84:87]
	v_mfma_f32_16x16x32_bf16 v[80:83], v[156:159], v[210:213], v[80:83]
	v_mfma_f32_16x16x32_bf16 v[76:79], v[148:151], v[218:221], v[76:79]
	v_mfma_f32_16x16x32_bf16 v[72:75], v[156:159], v[218:221], v[72:75]
	v_mfma_f32_16x16x32_bf16 v[68:71], v[148:151], v[226:229], v[68:71]
	v_mfma_f32_16x16x32_bf16 v[64:67], v[156:159], v[226:229], v[64:67]
	v_mfma_f32_16x16x32_bf16 v[92:95], v[152:155], v[206:209], v[92:95]
	v_mfma_f32_16x16x32_bf16 v[88:91], v[160:163], v[206:209], v[88:91]
	v_mfma_f32_16x16x32_bf16 v[84:87], v[152:155], v[214:217], v[84:87]
	v_mfma_f32_16x16x32_bf16 v[80:83], v[160:163], v[214:217], v[80:83]
	v_mfma_f32_16x16x32_bf16 v[76:79], v[152:155], v[222:225], v[76:79]
	v_mfma_f32_16x16x32_bf16 v[72:75], v[160:163], v[222:225], v[72:75]
	v_mfma_f32_16x16x32_bf16 v[68:71], v[152:155], v[238:241], v[68:71]
	v_mfma_f32_16x16x32_bf16 v[64:67], v[160:163], v[238:241], v[64:67]
	v_mfma_f32_16x16x32_bf16 v[28:31], v[164:167], v[202:205], v[28:31]
	v_mfma_f32_16x16x32_bf16 v[24:27], v[172:175], v[202:205], v[24:27]
	v_mfma_f32_16x16x32_bf16 v[20:23], v[164:167], v[210:213], v[20:23]
	v_mfma_f32_16x16x32_bf16 v[16:19], v[172:175], v[210:213], v[16:19]
	v_mfma_f32_16x16x32_bf16 v[12:15], v[164:167], v[218:221], v[12:15]
	v_mfma_f32_16x16x32_bf16 v[8:11], v[172:175], v[218:221], v[8:11]
	v_mfma_f32_16x16x32_bf16 v[4:7], v[164:167], v[226:229], v[4:7]
	v_mfma_f32_16x16x32_bf16 v[0:3], v[172:175], v[226:229], v[0:3]
	v_mfma_f32_16x16x32_bf16 v[28:31], v[168:171], v[206:209], v[28:31]
	v_mfma_f32_16x16x32_bf16 v[24:27], v[198:201], v[206:209], v[24:27]
	v_mfma_f32_16x16x32_bf16 v[20:23], v[168:171], v[214:217], v[20:23]
	v_mfma_f32_16x16x32_bf16 v[16:19], v[198:201], v[214:217], v[16:19]
	v_mfma_f32_16x16x32_bf16 v[12:15], v[168:171], v[222:225], v[12:15]
	v_mfma_f32_16x16x32_bf16 v[8:11], v[198:201], v[222:225], v[8:11]
	v_mfma_f32_16x16x32_bf16 v[4:7], v[168:171], v[238:241], v[4:7]
	v_mfma_f32_16x16x32_bf16 v[0:3], v[198:201], v[238:241], v[0:3]
	s_setprio 0
	s_barrier
	s_add_i32 s30, 0, 0x18000
	v_add_u32_e32 v147, s30, v141
	s_add_i32 s31, 0, 0x1c000
	ds_read_b128 v[148:151], v147
	ds_read_b128 v[152:155], v147 offset:1024
	ds_read_b128 v[156:159], v147 offset:2048
	ds_read_b128 v[160:163], v147 offset:3072
	v_add_u32_e32 v147, s31, v141
	ds_read_b128 v[164:167], v147
	ds_read_b128 v[168:171], v147 offset:1024
	ds_read_b128 v[172:175], v147 offset:2048
	ds_read_b128 v[198:201], v147 offset:3072
	s_add_u32 s10, s36, 0x18000
	s_addc_u32 s11, s37, 0
	s_mov_b32 m0, s41
	v_lshl_add_u64 v[246:247], s[10:11], 0, v[130:131]
	ds_read_b128 v[202:205], v145 offset:32768
	ds_read_b128 v[206:209], v145 offset:33792
	ds_read_b128 v[210:213], v145 offset:34816
	ds_read_b128 v[214:217], v145 offset:35840
	ds_read_b128 v[218:221], v145 offset:36864
	ds_read_b128 v[222:225], v145 offset:37888
	ds_read_b128 v[226:229], v145 offset:38912
	ds_read_b128 v[238:241], v145 offset:39936
	global_load_lds_dwordx4 v[246:247], off
	v_lshl_add_u64 v[246:247], s[10:11], 0, v[132:133]
	s_mov_b32 m0, s42
	s_nop 0
	global_load_lds_dwordx4 v[246:247], off
	s_waitcnt vmcnt(8) lgkmcnt(0)
	s_barrier
	s_setprio 1
	v_mfma_f32_16x16x32_bf16 v[124:127], v[148:151], v[202:205], v[124:127]
	v_mfma_f32_16x16x32_bf16 v[120:123], v[156:159], v[202:205], v[120:123]
	v_mfma_f32_16x16x32_bf16 v[116:119], v[148:151], v[210:213], v[116:119]
	v_mfma_f32_16x16x32_bf16 v[112:115], v[156:159], v[210:213], v[112:115]
	v_mfma_f32_16x16x32_bf16 v[108:111], v[148:151], v[218:221], v[108:111]
	v_mfma_f32_16x16x32_bf16 v[104:107], v[156:159], v[218:221], v[104:107]
	v_mfma_f32_16x16x32_bf16 v[100:103], v[148:151], v[226:229], v[100:103]
	v_mfma_f32_16x16x32_bf16 v[96:99], v[156:159], v[226:229], v[96:99]
	v_mfma_f32_16x16x32_bf16 v[124:127], v[152:155], v[206:209], v[124:127]
	v_mfma_f32_16x16x32_bf16 v[120:123], v[160:163], v[206:209], v[120:123]
	v_mfma_f32_16x16x32_bf16 v[116:119], v[152:155], v[214:217], v[116:119]
	v_mfma_f32_16x16x32_bf16 v[112:115], v[160:163], v[214:217], v[112:115]
	v_mfma_f32_16x16x32_bf16 v[108:111], v[152:155], v[222:225], v[108:111]
	v_mfma_f32_16x16x32_bf16 v[104:107], v[160:163], v[222:225], v[104:107]
	v_mfma_f32_16x16x32_bf16 v[100:103], v[152:155], v[238:241], v[100:103]
	v_mfma_f32_16x16x32_bf16 v[96:99], v[160:163], v[238:241], v[96:99]
	v_mfma_f32_16x16x32_bf16 v[60:63], v[164:167], v[202:205], v[60:63]
	v_mfma_f32_16x16x32_bf16 v[56:59], v[172:175], v[202:205], v[56:59]
	v_mfma_f32_16x16x32_bf16 v[52:55], v[164:167], v[210:213], v[52:55]
	v_mfma_f32_16x16x32_bf16 v[48:51], v[172:175], v[210:213], v[48:51]
	v_mfma_f32_16x16x32_bf16 v[44:47], v[164:167], v[218:221], v[44:47]
	v_mfma_f32_16x16x32_bf16 v[40:43], v[172:175], v[218:221], v[40:43]
	v_mfma_f32_16x16x32_bf16 v[36:39], v[164:167], v[226:229], v[36:39]
	v_mfma_f32_16x16x32_bf16 v[32:35], v[172:175], v[226:229], v[32:35]
	v_mfma_f32_16x16x32_bf16 v[60:63], v[168:171], v[206:209], v[60:63]
	v_mfma_f32_16x16x32_bf16 v[56:59], v[198:201], v[206:209], v[56:59]
	v_mfma_f32_16x16x32_bf16 v[52:55], v[168:171], v[214:217], v[52:55]
	v_mfma_f32_16x16x32_bf16 v[48:51], v[198:201], v[214:217], v[48:51]
	v_mfma_f32_16x16x32_bf16 v[44:47], v[168:171], v[222:225], v[44:47]
	v_mfma_f32_16x16x32_bf16 v[40:43], v[198:201], v[222:225], v[40:43]
	v_mfma_f32_16x16x32_bf16 v[36:39], v[168:171], v[238:241], v[36:39]
	v_mfma_f32_16x16x32_bf16 v[32:35], v[198:201], v[238:241], v[32:35]
	s_setprio 0
	s_barrier
	s_add_i32 s10, s30, s38
	v_lshl_add_u64 v[138:139], v[138:139], 0, s[90:91]
	s_mov_b32 m0, s10
	ds_read_b128 v[202:205], v145 offset:49152
	ds_read_b128 v[206:209], v145 offset:50176
	ds_read_b128 v[210:213], v145 offset:51200
	ds_read_b128 v[214:217], v145 offset:52224
	ds_read_b128 v[218:221], v145 offset:53248
	ds_read_b128 v[222:225], v145 offset:54272
	ds_read_b128 v[226:229], v145 offset:55296
	ds_read_b128 v[238:241], v145 offset:56320
	global_load_lds_dwordx4 v[138:139], off
	s_add_i32 m0, s10, 0x2000
	s_add_u32 s10, s34, 0x18080
	v_lshl_add_u64 v[138:139], v[176:177], 0, s[90:91]
	s_addc_u32 s11, s35, 0
	s_add_i32 s30, s31, s38
	global_load_lds_dwordx4 v[138:139], off
	v_lshl_add_u64 v[138:139], s[10:11], 0, v[130:131]
	s_mov_b32 m0, s30
	s_nop 0
	global_load_lds_dwordx4 v[138:139], off
	v_lshl_add_u64 v[138:139], s[10:11], 0, v[132:133]
	s_add_i32 m0, s30, 0x2000
	s_nop 0
	global_load_lds_dwordx4 v[138:139], off
	v_lshl_add_u64 v[138:139], v[242:243], 0, s[90:91]
	s_mov_b32 m0, s45
	s_nop 0
	global_load_lds_dwordx4 v[138:139], off
	v_lshl_add_u64 v[138:139], v[244:245], 0, s[90:91]
	s_mov_b32 m0, s46
	s_nop 0
	global_load_lds_dwordx4 v[138:139], off
	s_waitcnt vmcnt(8) lgkmcnt(0)
	s_barrier
	s_setprio 1
	v_mfma_f32_16x16x32_bf16 v[92:95], v[148:151], v[202:205], v[92:95]
	v_mfma_f32_16x16x32_bf16 v[88:91], v[156:159], v[202:205], v[88:91]
	v_mfma_f32_16x16x32_bf16 v[84:87], v[148:151], v[210:213], v[84:87]
	v_mfma_f32_16x16x32_bf16 v[80:83], v[156:159], v[210:213], v[80:83]
	v_mfma_f32_16x16x32_bf16 v[76:79], v[148:151], v[218:221], v[76:79]
	v_mfma_f32_16x16x32_bf16 v[72:75], v[156:159], v[218:221], v[72:75]
	v_mfma_f32_16x16x32_bf16 v[68:71], v[148:151], v[226:229], v[68:71]
	v_mfma_f32_16x16x32_bf16 v[64:67], v[156:159], v[226:229], v[64:67]
	v_mfma_f32_16x16x32_bf16 v[92:95], v[152:155], v[206:209], v[92:95]
	v_mfma_f32_16x16x32_bf16 v[88:91], v[160:163], v[206:209], v[88:91]
	v_mfma_f32_16x16x32_bf16 v[84:87], v[152:155], v[214:217], v[84:87]
	v_mfma_f32_16x16x32_bf16 v[80:83], v[160:163], v[214:217], v[80:83]
	v_mfma_f32_16x16x32_bf16 v[76:79], v[152:155], v[222:225], v[76:79]
	v_mfma_f32_16x16x32_bf16 v[72:75], v[160:163], v[222:225], v[72:75]
	v_mfma_f32_16x16x32_bf16 v[68:71], v[152:155], v[238:241], v[68:71]
	v_mfma_f32_16x16x32_bf16 v[64:67], v[160:163], v[238:241], v[64:67]
	v_mfma_f32_16x16x32_bf16 v[28:31], v[164:167], v[202:205], v[28:31]
	v_mfma_f32_16x16x32_bf16 v[24:27], v[172:175], v[202:205], v[24:27]
	v_mfma_f32_16x16x32_bf16 v[20:23], v[164:167], v[210:213], v[20:23]
	v_mfma_f32_16x16x32_bf16 v[16:19], v[172:175], v[210:213], v[16:19]
	v_mfma_f32_16x16x32_bf16 v[12:15], v[164:167], v[218:221], v[12:15]
	v_mfma_f32_16x16x32_bf16 v[8:11], v[172:175], v[218:221], v[8:11]
	v_mfma_f32_16x16x32_bf16 v[4:7], v[164:167], v[226:229], v[4:7]
	v_mfma_f32_16x16x32_bf16 v[0:3], v[172:175], v[226:229], v[0:3]
	v_mfma_f32_16x16x32_bf16 v[28:31], v[168:171], v[206:209], v[28:31]
	v_mfma_f32_16x16x32_bf16 v[24:27], v[198:201], v[206:209], v[24:27]
	v_mfma_f32_16x16x32_bf16 v[20:23], v[168:171], v[214:217], v[20:23]
	v_mfma_f32_16x16x32_bf16 v[16:19], v[198:201], v[214:217], v[16:19]
	v_mfma_f32_16x16x32_bf16 v[12:15], v[168:171], v[222:225], v[12:15]
	v_mfma_f32_16x16x32_bf16 v[8:11], v[198:201], v[222:225], v[8:11]
	v_mfma_f32_16x16x32_bf16 v[4:7], v[168:171], v[238:241], v[4:7]
	v_mfma_f32_16x16x32_bf16 v[0:3], v[198:201], v[238:241], v[0:3]
	s_setprio 0
	s_barrier
	s_add_i32 s55, s55, 2
	s_add_u32 s52, s52, 0x100
	s_addc_u32 s53, s53, 0
	s_cmp_gt_u32 s55, 3
	s_mov_b64 s[10:11], s[8:9]
	s_cbranch_scc0 .LBB0_296
	s_and_b64 vcc, exec, s[24:25]
	s_cbranch_vccz .LBB0_299
	s_barrier

.LBB0_344:
	s_add_u32 s47, s34, s46
	s_addc_u32 s59, s35, 0
	s_add_u32 s48, s47, 0x100
	s_addc_u32 s49, s59, 0
	s_and_b64 s[30:31], s[44:45], exec
	s_cselect_b32 s49, s19, s49
	s_cselect_b32 s48, s57, s48
	s_add_u32 s30, s36, s46
	s_addc_u32 s31, s37, 0
	s_add_u32 s46, s30, 0x100
	s_addc_u32 s50, s31, 0
	s_add_i32 s74, 0, 0x10000
	s_and_b64 s[30:31], s[44:45], exec
	s_cselect_b32 s51, s17, s50
	s_cselect_b32 s50, s58, s46
	s_add_i32 s45, 0, 0x14000
	s_add_u32 s30, s47, 0x10080
	s_addc_u32 s31, s59, 0
	s_add_i32 s83, s74, s40
	s_add_i32 m0, s20, 0xc000
	s_add_i32 s82, s20, 0xe000
	s_add_i32 s84, s83, 0x2000
	s_add_u32 s60, s50, 0x10000
	v_add_u32_e32 v152, s74, v137
	v_add_u32_e32 v168, s45, v137
	s_addc_u32 s61, s51, 0
	s_add_i32 s85, s45, s40
	ds_read_b128 v[140:143], v152
	ds_read_b128 v[144:147], v152 offset:1024
	ds_read_b128 v[148:151], v152 offset:2048
	ds_read_b128 v[152:155], v152 offset:3072
	ds_read_b128 v[156:159], v168
	ds_read_b128 v[160:163], v168 offset:1024
	ds_read_b128 v[164:167], v168 offset:2048
	ds_read_b128 v[168:171], v168 offset:3072
	s_add_i32 s86, s85, 0x2000
	s_add_i32 s87, 0, 0x18000
	s_add_i32 s88, 0, 0x1c000
	s_add_u32 s46, s48, 0x10000
	s_addc_u32 s47, s49, 0
	s_add_i32 s73, s87, s40
	s_add_i32 s59, s73, 0x2000
	s_add_u32 s44, s50, 0x10080
	s_addc_u32 s45, s51, 0
	s_add_i32 s81, s88, s40
	s_add_i32 s74, s81, 0x2000
	v_lshl_add_u64 v[176:177], s[30:31], 0, v[134:135]
	ds_read_b128 v[172:175], v139
	ds_read_b128 v[198:201], v139 offset:1024
	ds_read_b128 v[202:205], v139 offset:2048
	ds_read_b128 v[206:209], v139 offset:3072
	ds_read_b128 v[210:213], v139 offset:4096
	ds_read_b128 v[214:217], v139 offset:5120
	ds_read_b128 v[218:221], v139 offset:6144
	ds_read_b128 v[222:225], v139 offset:7168
	global_load_lds_dwordx4 v[176:177], off
	v_lshl_add_u64 v[176:177], s[30:31], 0, v[132:133]
	s_mov_b32 m0, s82
	s_nop 0
	global_load_lds_dwordx4 v[176:177], off
	s_waitcnt vmcnt(8) lgkmcnt(0)
	s_barrier
	s_setprio 1
	v_mfma_f32_16x16x32_bf16 v[112:115], v[140:143], v[172:175], v[112:115]
	v_mfma_f32_16x16x32_bf16 v[116:119], v[148:151], v[172:175], v[116:119]
	v_mfma_f32_16x16x32_bf16 v[96:99], v[140:143], v[202:205], v[96:99]
	v_mfma_f32_16x16x32_bf16 v[100:103], v[148:151], v[202:205], v[100:103]
	v_mfma_f32_16x16x32_bf16 v[72:75], v[140:143], v[210:213], v[72:75]
	v_mfma_f32_16x16x32_bf16 v[80:83], v[148:151], v[210:213], v[80:83]
	v_mfma_f32_16x16x32_bf16 v[40:43], v[140:143], v[218:221], v[40:43]
	v_mfma_f32_16x16x32_bf16 v[48:51], v[148:151], v[218:221], v[48:51]
	v_mfma_f32_16x16x32_bf16 v[112:115], v[144:147], v[198:201], v[112:115]
	v_mfma_f32_16x16x32_bf16 v[116:119], v[152:155], v[198:201], v[116:119]
	v_mfma_f32_16x16x32_bf16 v[96:99], v[144:147], v[206:209], v[96:99]
	v_mfma_f32_16x16x32_bf16 v[100:103], v[152:155], v[206:209], v[100:103]
	v_mfma_f32_16x16x32_bf16 v[72:75], v[144:147], v[214:217], v[72:75]
	v_mfma_f32_16x16x32_bf16 v[80:83], v[152:155], v[214:217], v[80:83]
	v_mfma_f32_16x16x32_bf16 v[40:43], v[144:147], v[222:225], v[40:43]
	v_mfma_f32_16x16x32_bf16 v[48:51], v[152:155], v[222:225], v[48:51]
	v_mfma_f32_16x16x32_bf16 v[120:123], v[156:159], v[172:175], v[120:123]
	v_mfma_f32_16x16x32_bf16 v[124:127], v[164:167], v[172:175], v[124:127]
	v_mfma_f32_16x16x32_bf16 v[104:107], v[156:159], v[202:205], v[104:107]
	v_mfma_f32_16x16x32_bf16 v[108:111], v[164:167], v[202:205], v[108:111]
	v_mfma_f32_16x16x32_bf16 v[88:91], v[156:159], v[210:213], v[88:91]
	v_mfma_f32_16x16x32_bf16 v[92:95], v[164:167], v[210:213], v[92:95]
	v_mfma_f32_16x16x32_bf16 v[64:67], v[156:159], v[218:221], v[64:67]
	v_mfma_f32_16x16x32_bf16 v[68:71], v[164:167], v[218:221], v[68:71]
	v_mfma_f32_16x16x32_bf16 v[120:123], v[160:163], v[198:201], v[120:123]
	v_mfma_f32_16x16x32_bf16 v[124:127], v[168:171], v[198:201], v[124:127]
	v_mfma_f32_16x16x32_bf16 v[104:107], v[160:163], v[206:209], v[104:107]
	v_mfma_f32_16x16x32_bf16 v[108:111], v[168:171], v[206:209], v[108:111]
	v_mfma_f32_16x16x32_bf16 v[88:91], v[160:163], v[214:217], v[88:91]
	v_mfma_f32_16x16x32_bf16 v[92:95], v[168:171], v[214:217], v[92:95]
	v_mfma_f32_16x16x32_bf16 v[64:67], v[160:163], v[222:225], v[64:67]
	v_mfma_f32_16x16x32_bf16 v[68:71], v[168:171], v[222:225], v[68:71]
	s_setprio 0
	s_barrier
	s_mov_b32 m0, s83
	v_lshl_add_u64 v[176:177], s[50:51], 0, v[128:129]
	ds_read_b128 v[172:175], v139 offset:16384
	ds_read_b128 v[198:201], v139 offset:17408
	ds_read_b128 v[202:205], v139 offset:18432
	ds_read_b128 v[206:209], v139 offset:19456
	ds_read_b128 v[210:213], v139 offset:20480
	ds_read_b128 v[214:217], v139 offset:21504
	ds_read_b128 v[218:221], v139 offset:22528
	ds_read_b128 v[222:225], v139 offset:23552
	global_load_lds_dwordx4 v[176:177], off
	v_lshl_add_u64 v[226:227], s[50:51], 0, v[130:131]
	s_mov_b32 m0, s84
	v_lshl_add_u64 v[228:229], s[60:61], 0, v[128:129]
	global_load_lds_dwordx4 v[226:227], off
	s_mov_b32 m0, s85
	v_lshl_add_u64 v[238:239], s[48:49], 0, v[132:133]
	global_load_lds_dwordx4 v[228:229], off
	v_lshl_add_u64 v[228:229], s[60:61], 0, v[130:131]
	s_mov_b32 m0, s86
	s_nop 0
	global_load_lds_dwordx4 v[228:229], off
	v_lshl_add_u64 v[228:229], s[48:49], 0, v[134:135]
	s_mov_b32 m0, s20
	s_nop 0
	global_load_lds_dwordx4 v[228:229], off
	s_mov_b32 m0, s21
	s_nop 0
	global_load_lds_dwordx4 v[238:239], off
	s_waitcnt vmcnt(8) lgkmcnt(0)
	s_barrier
	s_setprio 1
	v_mfma_f32_16x16x32_bf16 v[56:59], v[140:143], v[172:175], v[56:59]
	v_mfma_f32_16x16x32_bf16 v[60:63], v[148:151], v[172:175], v[60:63]
	v_mfma_f32_16x16x32_bf16 v[32:35], v[140:143], v[202:205], v[32:35]
	v_mfma_f32_16x16x32_bf16 v[36:39], v[148:151], v[202:205], v[36:39]
	v_mfma_f32_16x16x32_bf16 v[16:19], v[140:143], v[210:213], v[16:19]
	v_mfma_f32_16x16x32_bf16 v[20:23], v[148:151], v[210:213], v[20:23]
	v_mfma_f32_16x16x32_bf16 v[0:3], v[140:143], v[218:221], v[0:3]
	v_mfma_f32_16x16x32_bf16 v[4:7], v[148:151], v[218:221], v[4:7]
	v_mfma_f32_16x16x32_bf16 v[56:59], v[144:147], v[198:201], v[56:59]
	v_mfma_f32_16x16x32_bf16 v[60:63], v[152:155], v[198:201], v[60:63]
	v_mfma_f32_16x16x32_bf16 v[32:35], v[144:147], v[206:209], v[32:35]
	v_mfma_f32_16x16x32_bf16 v[36:39], v[152:155], v[206:209], v[36:39]
	v_mfma_f32_16x16x32_bf16 v[16:19], v[144:147], v[214:217], v[16:19]
	v_mfma_f32_16x16x32_bf16 v[20:23], v[152:155], v[214:217], v[20:23]
	v_mfma_f32_16x16x32_bf16 v[0:3], v[144:147], v[222:225], v[0:3]
	v_mfma_f32_16x16x32_bf16 v[4:7], v[152:155], v[222:225], v[4:7]
	v_mfma_f32_16x16x32_bf16 v[76:79], v[156:159], v[172:175], v[76:79]
	v_mfma_f32_16x16x32_bf16 v[84:87], v[164:167], v[172:175], v[84:87]
	v_mfma_f32_16x16x32_bf16 v[44:47], v[156:159], v[202:205], v[44:47]
	v_mfma_f32_16x16x32_bf16 v[52:55], v[164:167], v[202:205], v[52:55]
	v_mfma_f32_16x16x32_bf16 v[24:27], v[156:159], v[210:213], v[24:27]
	v_mfma_f32_16x16x32_bf16 v[28:31], v[164:167], v[210:213], v[28:31]
	v_mfma_f32_16x16x32_bf16 v[8:11], v[156:159], v[218:221], v[8:11]
	v_mfma_f32_16x16x32_bf16 v[12:15], v[164:167], v[218:221], v[12:15]
	v_mfma_f32_16x16x32_bf16 v[76:79], v[160:163], v[198:201], v[76:79]
	v_mfma_f32_16x16x32_bf16 v[84:87], v[168:171], v[198:201], v[84:87]
	v_mfma_f32_16x16x32_bf16 v[44:47], v[160:163], v[206:209], v[44:47]
	v_mfma_f32_16x16x32_bf16 v[52:55], v[168:171], v[206:209], v[52:55]
	v_mfma_f32_16x16x32_bf16 v[24:27], v[160:163], v[214:217], v[24:27]
	v_mfma_f32_16x16x32_bf16 v[28:31], v[168:171], v[214:217], v[28:31]
	v_mfma_f32_16x16x32_bf16 v[8:11], v[160:163], v[222:225], v[8:11]
	v_mfma_f32_16x16x32_bf16 v[12:15], v[168:171], v[222:225], v[12:15]
	s_setprio 0
	s_barrier
	v_add_u32_e32 v152, s87, v137
	v_add_u32_e32 v168, s88, v137
	ds_read_b128 v[140:143], v152
	ds_read_b128 v[144:147], v152 offset:1024
	ds_read_b128 v[148:151], v152 offset:2048
	ds_read_b128 v[152:155], v152 offset:3072
	ds_read_b128 v[156:159], v168
	ds_read_b128 v[160:163], v168 offset:1024
	ds_read_b128 v[164:167], v168 offset:2048
	ds_read_b128 v[168:171], v168 offset:3072
	s_mov_b32 m0, s25
	v_lshl_add_u64 v[240:241], s[46:47], 0, v[134:135]
	ds_read_b128 v[172:175], v139 offset:32768
	ds_read_b128 v[198:201], v139 offset:33792
	ds_read_b128 v[202:205], v139 offset:34816
	ds_read_b128 v[206:209], v139 offset:35840
	ds_read_b128 v[210:213], v139 offset:36864
	ds_read_b128 v[214:217], v139 offset:37888
	ds_read_b128 v[218:221], v139 offset:38912
	ds_read_b128 v[222:225], v139 offset:39936
	global_load_lds_dwordx4 v[240:241], off
	v_lshl_add_u64 v[240:241], s[46:47], 0, v[132:133]
	s_mov_b32 m0, s42
	s_nop 0
	global_load_lds_dwordx4 v[240:241], off
	s_waitcnt vmcnt(8) lgkmcnt(0)
	s_barrier
	s_setprio 1
	v_mfma_f32_16x16x32_bf16 v[112:115], v[140:143], v[172:175], v[112:115]
	v_mfma_f32_16x16x32_bf16 v[116:119], v[148:151], v[172:175], v[116:119]
	v_mfma_f32_16x16x32_bf16 v[96:99], v[140:143], v[202:205], v[96:99]
	v_mfma_f32_16x16x32_bf16 v[100:103], v[148:151], v[202:205], v[100:103]
	v_mfma_f32_16x16x32_bf16 v[72:75], v[140:143], v[210:213], v[72:75]
	v_mfma_f32_16x16x32_bf16 v[80:83], v[148:151], v[210:213], v[80:83]
	v_mfma_f32_16x16x32_bf16 v[40:43], v[140:143], v[218:221], v[40:43]
	v_mfma_f32_16x16x32_bf16 v[48:51], v[148:151], v[218:221], v[48:51]
	v_mfma_f32_16x16x32_bf16 v[112:115], v[144:147], v[198:201], v[112:115]
	v_mfma_f32_16x16x32_bf16 v[116:119], v[152:155], v[198:201], v[116:119]
	v_mfma_f32_16x16x32_bf16 v[96:99], v[144:147], v[206:209], v[96:99]
	v_mfma_f32_16x16x32_bf16 v[100:103], v[152:155], v[206:209], v[100:103]
	v_mfma_f32_16x16x32_bf16 v[72:75], v[144:147], v[214:217], v[72:75]
	v_mfma_f32_16x16x32_bf16 v[80:83], v[152:155], v[214:217], v[80:83]
	v_mfma_f32_16x16x32_bf16 v[40:43], v[144:147], v[222:225], v[40:43]
	v_mfma_f32_16x16x32_bf16 v[48:51], v[152:155], v[222:225], v[48:51]
	v_mfma_f32_16x16x32_bf16 v[120:123], v[156:159], v[172:175], v[120:123]
	v_mfma_f32_16x16x32_bf16 v[124:127], v[164:167], v[172:175], v[124:127]
	v_mfma_f32_16x16x32_bf16 v[104:107], v[156:159], v[202:205], v[104:107]
	v_mfma_f32_16x16x32_bf16 v[108:111], v[164:167], v[202:205], v[108:111]
	v_mfma_f32_16x16x32_bf16 v[88:91], v[156:159], v[210:213], v[88:91]
	v_mfma_f32_16x16x32_bf16 v[92:95], v[164:167], v[210:213], v[92:95]
	v_mfma_f32_16x16x32_bf16 v[64:67], v[156:159], v[218:221], v[64:67]
	v_mfma_f32_16x16x32_bf16 v[68:71], v[164:167], v[218:221], v[68:71]
	v_mfma_f32_16x16x32_bf16 v[120:123], v[160:163], v[198:201], v[120:123]
	v_mfma_f32_16x16x32_bf16 v[124:127], v[168:171], v[198:201], v[124:127]
	v_mfma_f32_16x16x32_bf16 v[104:107], v[160:163], v[206:209], v[104:107]
	v_mfma_f32_16x16x32_bf16 v[108:111], v[168:171], v[206:209], v[108:111]
	v_mfma_f32_16x16x32_bf16 v[88:91], v[160:163], v[214:217], v[88:91]
	v_mfma_f32_16x16x32_bf16 v[92:95], v[168:171], v[214:217], v[92:95]
	v_mfma_f32_16x16x32_bf16 v[64:67], v[160:163], v[222:225], v[64:67]
	v_mfma_f32_16x16x32_bf16 v[68:71], v[168:171], v[222:225], v[68:71]
	s_setprio 0
	s_barrier
	s_mov_b32 m0, s73
	v_lshl_add_u64 v[176:177], v[176:177], 0, s[90:91]
	ds_read_b128 v[172:175], v139 offset:49152
	ds_read_b128 v[198:201], v139 offset:50176
	ds_read_b128 v[202:205], v139 offset:51200
	ds_read_b128 v[206:209], v139 offset:52224
	ds_read_b128 v[210:213], v139 offset:53248
	ds_read_b128 v[214:217], v139 offset:54272
	ds_read_b128 v[218:221], v139 offset:55296
	ds_read_b128 v[222:225], v139 offset:56320
	global_load_lds_dwordx4 v[176:177], off
	v_lshl_add_u64 v[176:177], v[226:227], 0, s[90:91]
	s_mov_b32 m0, s59
	s_nop 0
	global_load_lds_dwordx4 v[176:177], off
	v_lshl_add_u64 v[176:177], s[44:45], 0, v[128:129]
	s_mov_b32 m0, s81
	s_nop 0
	global_load_lds_dwordx4 v[176:177], off
	v_lshl_add_u64 v[176:177], s[44:45], 0, v[130:131]
	s_mov_b32 m0, s74
	s_nop 0
	global_load_lds_dwordx4 v[176:177], off
	v_lshl_add_u64 v[176:177], v[228:229], 0, s[90:91]
	s_mov_b32 m0, s43
	s_nop 0
	global_load_lds_dwordx4 v[176:177], off
	v_lshl_add_u64 v[176:177], v[238:239], 0, s[90:91]
	s_mov_b32 m0, s52
	s_nop 0
	global_load_lds_dwordx4 v[176:177], off
	s_waitcnt vmcnt(8) lgkmcnt(0)
	s_barrier
	s_setprio 1
	v_mfma_f32_16x16x32_bf16 v[56:59], v[140:143], v[172:175], v[56:59]
	v_mfma_f32_16x16x32_bf16 v[60:63], v[148:151], v[172:175], v[60:63]
	v_mfma_f32_16x16x32_bf16 v[32:35], v[140:143], v[202:205], v[32:35]
	v_mfma_f32_16x16x32_bf16 v[36:39], v[148:151], v[202:205], v[36:39]
	v_mfma_f32_16x16x32_bf16 v[16:19], v[140:143], v[210:213], v[16:19]
	v_mfma_f32_16x16x32_bf16 v[20:23], v[148:151], v[210:213], v[20:23]
	v_mfma_f32_16x16x32_bf16 v[0:3], v[140:143], v[218:221], v[0:3]
	v_mfma_f32_16x16x32_bf16 v[4:7], v[148:151], v[218:221], v[4:7]
	v_mfma_f32_16x16x32_bf16 v[56:59], v[144:147], v[198:201], v[56:59]
	v_mfma_f32_16x16x32_bf16 v[60:63], v[152:155], v[198:201], v[60:63]
	v_mfma_f32_16x16x32_bf16 v[32:35], v[144:147], v[206:209], v[32:35]
	v_mfma_f32_16x16x32_bf16 v[36:39], v[152:155], v[206:209], v[36:39]
	v_mfma_f32_16x16x32_bf16 v[16:19], v[144:147], v[214:217], v[16:19]
	v_mfma_f32_16x16x32_bf16 v[20:23], v[152:155], v[214:217], v[20:23]
	v_mfma_f32_16x16x32_bf16 v[0:3], v[144:147], v[222:225], v[0:3]
	v_mfma_f32_16x16x32_bf16 v[4:7], v[152:155], v[222:225], v[4:7]
	v_mfma_f32_16x16x32_bf16 v[76:79], v[156:159], v[172:175], v[76:79]
	v_mfma_f32_16x16x32_bf16 v[84:87], v[164:167], v[172:175], v[84:87]
	v_mfma_f32_16x16x32_bf16 v[44:47], v[156:159], v[202:205], v[44:47]
	v_mfma_f32_16x16x32_bf16 v[52:55], v[164:167], v[202:205], v[52:55]
	v_mfma_f32_16x16x32_bf16 v[24:27], v[156:159], v[210:213], v[24:27]
	v_mfma_f32_16x16x32_bf16 v[28:31], v[164:167], v[210:213], v[28:31]
	v_mfma_f32_16x16x32_bf16 v[8:11], v[156:159], v[218:221], v[8:11]
	v_mfma_f32_16x16x32_bf16 v[12:15], v[164:167], v[218:221], v[12:15]
	v_mfma_f32_16x16x32_bf16 v[76:79], v[160:163], v[198:201], v[76:79]
	v_mfma_f32_16x16x32_bf16 v[84:87], v[168:171], v[198:201], v[84:87]
	v_mfma_f32_16x16x32_bf16 v[44:47], v[160:163], v[206:209], v[44:47]
	v_mfma_f32_16x16x32_bf16 v[52:55], v[168:171], v[206:209], v[52:55]
	v_mfma_f32_16x16x32_bf16 v[24:27], v[160:163], v[214:217], v[24:27]
	v_mfma_f32_16x16x32_bf16 v[28:31], v[168:171], v[214:217], v[28:31]
	v_mfma_f32_16x16x32_bf16 v[8:11], v[160:163], v[222:225], v[8:11]
	v_mfma_f32_16x16x32_bf16 v[12:15], v[168:171], v[222:225], v[12:15]
	s_setprio 0
	s_barrier
	s_movk_i32 s46, 0x100
	s_andn2_b64 vcc, exec, s[38:39]
	s_mov_b64 s[44:45], -1
	s_mov_b64 s[38:39], 0
	s_cbranch_vccz .LBB0_344
	s_and_b64 vcc, exec, s[14:15]
	s_cbranch_vccz .LBB0_347
	s_barrier

.LBB0_360:
	s_add_u32 s39, s18, s38
	s_addc_u32 s48, s19, 0
	s_add_u32 s44, s39, 0x100
	s_addc_u32 s45, s48, 0
	s_and_b64 s[30:31], s[36:37], exec
	s_cselect_b32 s45, s15, s45
	s_cselect_b32 s44, s55, s44
	s_add_u32 s30, s24, s38
	s_addc_u32 s31, s25, 0
	s_add_u32 s38, s30, 0x100
	s_addc_u32 s46, s31, 0
	s_add_i32 s59, 0, 0x10000
	s_and_b64 s[30:31], s[36:37], exec
	s_cselect_b32 s47, s13, s46
	s_cselect_b32 s46, s56, s38
	s_add_i32 s37, 0, 0x14000
	s_add_u32 s30, s39, 0x10080
	s_addc_u32 s31, s48, 0
	s_add_i32 s67, s59, s40
	s_add_i32 m0, s17, 0xc000
	s_add_i32 s61, s17, 0xe000
	s_add_i32 s73, s67, 0x2000
	s_add_u32 s48, s46, 0x10000
	v_add_u32_e32 v152, s59, v137
	v_add_u32_e32 v168, s37, v137
	s_addc_u32 s49, s47, 0
	s_add_i32 s74, s37, s40
	ds_read_b128 v[140:143], v152
	ds_read_b128 v[144:147], v152 offset:1024
	ds_read_b128 v[148:151], v152 offset:2048
	ds_read_b128 v[152:155], v152 offset:3072
	ds_read_b128 v[156:159], v168
	ds_read_b128 v[160:163], v168 offset:1024
	ds_read_b128 v[164:167], v168 offset:2048
	ds_read_b128 v[168:171], v168 offset:3072
	s_add_i32 s81, s74, 0x2000
	s_add_i32 s82, 0, 0x18000
	s_add_i32 s83, 0, 0x1c000
	s_add_u32 s38, s44, 0x10000
	s_addc_u32 s39, s45, 0
	s_add_i32 s58, s82, s40
	s_add_i32 s57, s58, 0x2000
	s_add_u32 s36, s46, 0x10080
	s_addc_u32 s37, s47, 0
	s_add_i32 s60, s83, s40
	s_add_i32 s59, s60, 0x2000
	v_lshl_add_u64 v[176:177], s[30:31], 0, v[134:135]
	ds_read_b128 v[172:175], v139
	ds_read_b128 v[198:201], v139 offset:1024
	ds_read_b128 v[202:205], v139 offset:2048
	ds_read_b128 v[206:209], v139 offset:3072
	ds_read_b128 v[210:213], v139 offset:4096
	ds_read_b128 v[214:217], v139 offset:5120
	ds_read_b128 v[218:221], v139 offset:6144
	ds_read_b128 v[222:225], v139 offset:7168
	global_load_lds_dwordx4 v[176:177], off
	v_lshl_add_u64 v[176:177], s[30:31], 0, v[132:133]
	s_mov_b32 m0, s61
	s_nop 0
	global_load_lds_dwordx4 v[176:177], off
	s_waitcnt vmcnt(8) lgkmcnt(0)
	s_barrier
	s_setprio 1
	v_mfma_f32_16x16x32_bf16 v[108:111], v[140:143], v[172:175], v[108:111]
	v_mfma_f32_16x16x32_bf16 v[116:119], v[148:151], v[172:175], v[116:119]
	v_mfma_f32_16x16x32_bf16 v[92:95], v[140:143], v[202:205], v[92:95]
	v_mfma_f32_16x16x32_bf16 v[100:103], v[148:151], v[202:205], v[100:103]
	v_mfma_f32_16x16x32_bf16 v[68:71], v[140:143], v[210:213], v[68:71]
	v_mfma_f32_16x16x32_bf16 v[76:79], v[148:151], v[210:213], v[76:79]
	v_mfma_f32_16x16x32_bf16 v[40:43], v[140:143], v[218:221], v[40:43]
	v_mfma_f32_16x16x32_bf16 v[44:47], v[148:151], v[218:221], v[44:47]
	v_mfma_f32_16x16x32_bf16 v[108:111], v[144:147], v[198:201], v[108:111]
	v_mfma_f32_16x16x32_bf16 v[116:119], v[152:155], v[198:201], v[116:119]
	v_mfma_f32_16x16x32_bf16 v[92:95], v[144:147], v[206:209], v[92:95]
	v_mfma_f32_16x16x32_bf16 v[100:103], v[152:155], v[206:209], v[100:103]
	v_mfma_f32_16x16x32_bf16 v[68:71], v[144:147], v[214:217], v[68:71]
	v_mfma_f32_16x16x32_bf16 v[76:79], v[152:155], v[214:217], v[76:79]
	v_mfma_f32_16x16x32_bf16 v[40:43], v[144:147], v[222:225], v[40:43]
	v_mfma_f32_16x16x32_bf16 v[44:47], v[152:155], v[222:225], v[44:47]
	v_mfma_f32_16x16x32_bf16 v[120:123], v[156:159], v[172:175], v[120:123]
	v_mfma_f32_16x16x32_bf16 v[124:127], v[164:167], v[172:175], v[124:127]
	v_mfma_f32_16x16x32_bf16 v[104:107], v[156:159], v[202:205], v[104:107]
	v_mfma_f32_16x16x32_bf16 v[112:115], v[164:167], v[202:205], v[112:115]
	v_mfma_f32_16x16x32_bf16 v[88:91], v[156:159], v[210:213], v[88:91]
	v_mfma_f32_16x16x32_bf16 v[96:99], v[164:167], v[210:213], v[96:99]
	v_mfma_f32_16x16x32_bf16 v[64:67], v[156:159], v[218:221], v[64:67]
	v_mfma_f32_16x16x32_bf16 v[72:75], v[164:167], v[218:221], v[72:75]
	v_mfma_f32_16x16x32_bf16 v[120:123], v[160:163], v[198:201], v[120:123]
	v_mfma_f32_16x16x32_bf16 v[124:127], v[168:171], v[198:201], v[124:127]
	v_mfma_f32_16x16x32_bf16 v[104:107], v[160:163], v[206:209], v[104:107]
	v_mfma_f32_16x16x32_bf16 v[112:115], v[168:171], v[206:209], v[112:115]
	v_mfma_f32_16x16x32_bf16 v[88:91], v[160:163], v[214:217], v[88:91]
	v_mfma_f32_16x16x32_bf16 v[96:99], v[168:171], v[214:217], v[96:99]
	v_mfma_f32_16x16x32_bf16 v[64:67], v[160:163], v[222:225], v[64:67]
	v_mfma_f32_16x16x32_bf16 v[72:75], v[168:171], v[222:225], v[72:75]
	s_setprio 0
	s_barrier
	s_mov_b32 m0, s67
	v_lshl_add_u64 v[176:177], s[46:47], 0, v[128:129]
	ds_read_b128 v[172:175], v139 offset:16384
	ds_read_b128 v[198:201], v139 offset:17408
	ds_read_b128 v[202:205], v139 offset:18432
	ds_read_b128 v[206:209], v139 offset:19456
	ds_read_b128 v[210:213], v139 offset:20480
	ds_read_b128 v[214:217], v139 offset:21504
	ds_read_b128 v[218:221], v139 offset:22528
	ds_read_b128 v[222:225], v139 offset:23552
	global_load_lds_dwordx4 v[176:177], off
	v_lshl_add_u64 v[226:227], s[46:47], 0, v[130:131]
	s_mov_b32 m0, s73
	v_lshl_add_u64 v[228:229], s[48:49], 0, v[128:129]
	global_load_lds_dwordx4 v[226:227], off
	s_mov_b32 m0, s74
	v_lshl_add_u64 v[238:239], s[44:45], 0, v[132:133]
	global_load_lds_dwordx4 v[228:229], off
	v_lshl_add_u64 v[228:229], s[48:49], 0, v[130:131]
	s_mov_b32 m0, s81
	s_nop 0
	global_load_lds_dwordx4 v[228:229], off
	v_lshl_add_u64 v[228:229], s[44:45], 0, v[134:135]
	s_mov_b32 m0, s17
	s_nop 0
	global_load_lds_dwordx4 v[228:229], off
	s_mov_b32 m0, s20
	s_nop 0
	global_load_lds_dwordx4 v[238:239], off
	s_waitcnt vmcnt(8) lgkmcnt(0)
	s_barrier
	s_setprio 1
	v_mfma_f32_16x16x32_bf16 v[52:55], v[140:143], v[172:175], v[52:55]
	v_mfma_f32_16x16x32_bf16 v[60:63], v[148:151], v[172:175], v[60:63]
	v_mfma_f32_16x16x32_bf16 v[28:31], v[140:143], v[202:205], v[28:31]
	v_mfma_f32_16x16x32_bf16 v[36:39], v[148:151], v[202:205], v[36:39]
	v_mfma_f32_16x16x32_bf16 v[12:15], v[140:143], v[210:213], v[12:15]
	v_mfma_f32_16x16x32_bf16 v[16:19], v[148:151], v[210:213], v[16:19]
	v_mfma_f32_16x16x32_bf16 v[0:3], v[140:143], v[218:221], v[0:3]
	v_mfma_f32_16x16x32_bf16 v[4:7], v[148:151], v[218:221], v[4:7]
	v_mfma_f32_16x16x32_bf16 v[52:55], v[144:147], v[198:201], v[52:55]
	v_mfma_f32_16x16x32_bf16 v[60:63], v[152:155], v[198:201], v[60:63]
	v_mfma_f32_16x16x32_bf16 v[28:31], v[144:147], v[206:209], v[28:31]
	v_mfma_f32_16x16x32_bf16 v[36:39], v[152:155], v[206:209], v[36:39]
	v_mfma_f32_16x16x32_bf16 v[12:15], v[144:147], v[214:217], v[12:15]
	v_mfma_f32_16x16x32_bf16 v[16:19], v[152:155], v[214:217], v[16:19]
	v_mfma_f32_16x16x32_bf16 v[0:3], v[144:147], v[222:225], v[0:3]
	v_mfma_f32_16x16x32_bf16 v[4:7], v[152:155], v[222:225], v[4:7]
	v_mfma_f32_16x16x32_bf16 v[80:83], v[156:159], v[172:175], v[80:83]
	v_mfma_f32_16x16x32_bf16 v[84:87], v[164:167], v[172:175], v[84:87]
	v_mfma_f32_16x16x32_bf16 v[48:51], v[156:159], v[202:205], v[48:51]
	v_mfma_f32_16x16x32_bf16 v[56:59], v[164:167], v[202:205], v[56:59]
	v_mfma_f32_16x16x32_bf16 v[24:27], v[156:159], v[210:213], v[24:27]
	v_mfma_f32_16x16x32_bf16 v[32:35], v[164:167], v[210:213], v[32:35]
	v_mfma_f32_16x16x32_bf16 v[8:11], v[156:159], v[218:221], v[8:11]
	v_mfma_f32_16x16x32_bf16 v[20:23], v[164:167], v[218:221], v[20:23]
	v_mfma_f32_16x16x32_bf16 v[80:83], v[160:163], v[198:201], v[80:83]
	v_mfma_f32_16x16x32_bf16 v[84:87], v[168:171], v[198:201], v[84:87]
	v_mfma_f32_16x16x32_bf16 v[48:51], v[160:163], v[206:209], v[48:51]
	v_mfma_f32_16x16x32_bf16 v[56:59], v[168:171], v[206:209], v[56:59]
	v_mfma_f32_16x16x32_bf16 v[24:27], v[160:163], v[214:217], v[24:27]
	v_mfma_f32_16x16x32_bf16 v[32:35], v[168:171], v[214:217], v[32:35]
	v_mfma_f32_16x16x32_bf16 v[8:11], v[160:163], v[222:225], v[8:11]
	v_mfma_f32_16x16x32_bf16 v[20:23], v[168:171], v[222:225], v[20:23]
	s_setprio 0
	s_barrier
	v_add_u32_e32 v152, s82, v137
	v_add_u32_e32 v168, s83, v137
	ds_read_b128 v[140:143], v152
	ds_read_b128 v[144:147], v152 offset:1024
	ds_read_b128 v[148:151], v152 offset:2048
	ds_read_b128 v[152:155], v152 offset:3072
	ds_read_b128 v[156:159], v168
	ds_read_b128 v[160:163], v168 offset:1024
	ds_read_b128 v[164:167], v168 offset:2048
	ds_read_b128 v[168:171], v168 offset:3072
	s_mov_b32 m0, s21
	v_lshl_add_u64 v[240:241], s[38:39], 0, v[134:135]
	ds_read_b128 v[172:175], v139 offset:32768
	ds_read_b128 v[198:201], v139 offset:33792
	ds_read_b128 v[202:205], v139 offset:34816
	ds_read_b128 v[206:209], v139 offset:35840
	ds_read_b128 v[210:213], v139 offset:36864
	ds_read_b128 v[214:217], v139 offset:37888
	ds_read_b128 v[218:221], v139 offset:38912
	ds_read_b128 v[222:225], v139 offset:39936
	global_load_lds_dwordx4 v[240:241], off
	v_lshl_add_u64 v[240:241], s[38:39], 0, v[132:133]
	s_mov_b32 m0, s42
	s_nop 0
	global_load_lds_dwordx4 v[240:241], off
	s_waitcnt vmcnt(8) lgkmcnt(0)
	s_barrier
	s_setprio 1
	v_mfma_f32_16x16x32_bf16 v[108:111], v[140:143], v[172:175], v[108:111]
	v_mfma_f32_16x16x32_bf16 v[116:119], v[148:151], v[172:175], v[116:119]
	v_mfma_f32_16x16x32_bf16 v[92:95], v[140:143], v[202:205], v[92:95]
	v_mfma_f32_16x16x32_bf16 v[100:103], v[148:151], v[202:205], v[100:103]
	v_mfma_f32_16x16x32_bf16 v[68:71], v[140:143], v[210:213], v[68:71]
	v_mfma_f32_16x16x32_bf16 v[76:79], v[148:151], v[210:213], v[76:79]
	v_mfma_f32_16x16x32_bf16 v[40:43], v[140:143], v[218:221], v[40:43]
	v_mfma_f32_16x16x32_bf16 v[44:47], v[148:151], v[218:221], v[44:47]
	v_mfma_f32_16x16x32_bf16 v[108:111], v[144:147], v[198:201], v[108:111]
	v_mfma_f32_16x16x32_bf16 v[116:119], v[152:155], v[198:201], v[116:119]
	v_mfma_f32_16x16x32_bf16 v[92:95], v[144:147], v[206:209], v[92:95]
	v_mfma_f32_16x16x32_bf16 v[100:103], v[152:155], v[206:209], v[100:103]
	v_mfma_f32_16x16x32_bf16 v[68:71], v[144:147], v[214:217], v[68:71]
	v_mfma_f32_16x16x32_bf16 v[76:79], v[152:155], v[214:217], v[76:79]
	v_mfma_f32_16x16x32_bf16 v[40:43], v[144:147], v[222:225], v[40:43]
	v_mfma_f32_16x16x32_bf16 v[44:47], v[152:155], v[222:225], v[44:47]
	v_mfma_f32_16x16x32_bf16 v[120:123], v[156:159], v[172:175], v[120:123]
	v_mfma_f32_16x16x32_bf16 v[124:127], v[164:167], v[172:175], v[124:127]
	v_mfma_f32_16x16x32_bf16 v[104:107], v[156:159], v[202:205], v[104:107]
	v_mfma_f32_16x16x32_bf16 v[112:115], v[164:167], v[202:205], v[112:115]
	v_mfma_f32_16x16x32_bf16 v[88:91], v[156:159], v[210:213], v[88:91]
	v_mfma_f32_16x16x32_bf16 v[96:99], v[164:167], v[210:213], v[96:99]
	v_mfma_f32_16x16x32_bf16 v[64:67], v[156:159], v[218:221], v[64:67]
	v_mfma_f32_16x16x32_bf16 v[72:75], v[164:167], v[218:221], v[72:75]
	v_mfma_f32_16x16x32_bf16 v[120:123], v[160:163], v[198:201], v[120:123]
	v_mfma_f32_16x16x32_bf16 v[124:127], v[168:171], v[198:201], v[124:127]
	v_mfma_f32_16x16x32_bf16 v[104:107], v[160:163], v[206:209], v[104:107]
	v_mfma_f32_16x16x32_bf16 v[112:115], v[168:171], v[206:209], v[112:115]
	v_mfma_f32_16x16x32_bf16 v[88:91], v[160:163], v[214:217], v[88:91]
	v_mfma_f32_16x16x32_bf16 v[96:99], v[168:171], v[214:217], v[96:99]
	v_mfma_f32_16x16x32_bf16 v[64:67], v[160:163], v[222:225], v[64:67]
	v_mfma_f32_16x16x32_bf16 v[72:75], v[168:171], v[222:225], v[72:75]
	s_setprio 0
	s_barrier
	s_mov_b32 m0, s58
	v_lshl_add_u64 v[176:177], v[176:177], 0, s[90:91]
	ds_read_b128 v[172:175], v139 offset:49152
	ds_read_b128 v[198:201], v139 offset:50176
	ds_read_b128 v[202:205], v139 offset:51200
	ds_read_b128 v[206:209], v139 offset:52224
	ds_read_b128 v[210:213], v139 offset:53248
	ds_read_b128 v[214:217], v139 offset:54272
	ds_read_b128 v[218:221], v139 offset:55296
	ds_read_b128 v[222:225], v139 offset:56320
	global_load_lds_dwordx4 v[176:177], off
	v_lshl_add_u64 v[176:177], v[226:227], 0, s[90:91]
	s_mov_b32 m0, s57
	s_nop 0
	global_load_lds_dwordx4 v[176:177], off
	v_lshl_add_u64 v[176:177], s[36:37], 0, v[128:129]
	s_mov_b32 m0, s60
	s_nop 0
	global_load_lds_dwordx4 v[176:177], off
	v_lshl_add_u64 v[176:177], s[36:37], 0, v[130:131]
	s_mov_b32 m0, s59
	s_nop 0
	global_load_lds_dwordx4 v[176:177], off
	v_lshl_add_u64 v[176:177], v[228:229], 0, s[90:91]
	s_mov_b32 m0, s43
	s_nop 0
	global_load_lds_dwordx4 v[176:177], off
	v_lshl_add_u64 v[176:177], v[238:239], 0, s[90:91]
	s_mov_b32 m0, s50
	s_nop 0
	global_load_lds_dwordx4 v[176:177], off
	s_waitcnt vmcnt(8) lgkmcnt(0)
	s_barrier
	s_setprio 1
	v_mfma_f32_16x16x32_bf16 v[52:55], v[140:143], v[172:175], v[52:55]
	v_mfma_f32_16x16x32_bf16 v[60:63], v[148:151], v[172:175], v[60:63]
	v_mfma_f32_16x16x32_bf16 v[28:31], v[140:143], v[202:205], v[28:31]
	v_mfma_f32_16x16x32_bf16 v[36:39], v[148:151], v[202:205], v[36:39]
	v_mfma_f32_16x16x32_bf16 v[12:15], v[140:143], v[210:213], v[12:15]
	v_mfma_f32_16x16x32_bf16 v[16:19], v[148:151], v[210:213], v[16:19]
	v_mfma_f32_16x16x32_bf16 v[0:3], v[140:143], v[218:221], v[0:3]
	v_mfma_f32_16x16x32_bf16 v[4:7], v[148:151], v[218:221], v[4:7]
	v_mfma_f32_16x16x32_bf16 v[52:55], v[144:147], v[198:201], v[52:55]
	v_mfma_f32_16x16x32_bf16 v[60:63], v[152:155], v[198:201], v[60:63]
	v_mfma_f32_16x16x32_bf16 v[28:31], v[144:147], v[206:209], v[28:31]
	v_mfma_f32_16x16x32_bf16 v[36:39], v[152:155], v[206:209], v[36:39]
	v_mfma_f32_16x16x32_bf16 v[12:15], v[144:147], v[214:217], v[12:15]
	v_mfma_f32_16x16x32_bf16 v[16:19], v[152:155], v[214:217], v[16:19]
	v_mfma_f32_16x16x32_bf16 v[0:3], v[144:147], v[222:225], v[0:3]
	v_mfma_f32_16x16x32_bf16 v[4:7], v[152:155], v[222:225], v[4:7]
	v_mfma_f32_16x16x32_bf16 v[80:83], v[156:159], v[172:175], v[80:83]
	v_mfma_f32_16x16x32_bf16 v[84:87], v[164:167], v[172:175], v[84:87]
	v_mfma_f32_16x16x32_bf16 v[48:51], v[156:159], v[202:205], v[48:51]
	v_mfma_f32_16x16x32_bf16 v[56:59], v[164:167], v[202:205], v[56:59]
	v_mfma_f32_16x16x32_bf16 v[24:27], v[156:159], v[210:213], v[24:27]
	v_mfma_f32_16x16x32_bf16 v[32:35], v[164:167], v[210:213], v[32:35]
	v_mfma_f32_16x16x32_bf16 v[8:11], v[156:159], v[218:221], v[8:11]
	v_mfma_f32_16x16x32_bf16 v[20:23], v[164:167], v[218:221], v[20:23]
	v_mfma_f32_16x16x32_bf16 v[80:83], v[160:163], v[198:201], v[80:83]
	v_mfma_f32_16x16x32_bf16 v[84:87], v[168:171], v[198:201], v[84:87]
	v_mfma_f32_16x16x32_bf16 v[48:51], v[160:163], v[206:209], v[48:51]
	v_mfma_f32_16x16x32_bf16 v[56:59], v[168:171], v[206:209], v[56:59]
	v_mfma_f32_16x16x32_bf16 v[24:27], v[160:163], v[214:217], v[24:27]
	v_mfma_f32_16x16x32_bf16 v[32:35], v[168:171], v[214:217], v[32:35]
	v_mfma_f32_16x16x32_bf16 v[8:11], v[160:163], v[222:225], v[8:11]
	v_mfma_f32_16x16x32_bf16 v[20:23], v[168:171], v[222:225], v[20:23]
	s_setprio 0
	s_barrier
	s_movk_i32 s38, 0x100
	s_andn2_b64 vcc, exec, s[34:35]
	s_mov_b64 s[36:37], -1
	s_mov_b64 s[34:35], 0
	s_cbranch_vccz .LBB0_360
	s_and_b64 vcc, exec, s[10:11]
	s_cbranch_vccz .LBB0_363
	s_barrier

.LBB0_395:
	s_add_u32 s16, s14, 0xfffc0080
	s_addc_u32 s17, s15, -1
	s_add_i32 s30, 0, 0x10000
	s_cmp_eq_u32 s48, 12
	s_cselect_b32 s27, s21, s17
	s_cselect_b32 s26, s44, s16
	v_add_u32_e32 v142, s30, v145
	s_cselect_b32 s17, s19, s47
	s_cselect_b32 s16, s45, s46
	s_add_i32 s49, 0, 0x14000
	ds_read_b128 v[146:149], v142
	ds_read_b128 v[150:153], v142 offset:1024
	ds_read_b128 v[154:157], v142 offset:2048
	ds_read_b128 v[158:161], v142 offset:3072
	v_add_u32_e32 v142, s49, v145
	ds_read_b128 v[162:165], v142
	ds_read_b128 v[166:169], v142 offset:1024
	ds_read_b128 v[170:173], v142 offset:2048
	ds_read_b128 v[174:177], v142 offset:3072
	v_lshl_add_u64 v[142:143], s[14:15], 0, v[138:139]
	s_add_i32 m0, s9, 0xc000
	ds_read_b128 v[198:201], v141
	ds_read_b128 v[202:205], v141 offset:1024
	ds_read_b128 v[206:209], v141 offset:2048
	ds_read_b128 v[210:213], v141 offset:3072
	ds_read_b128 v[214:217], v141 offset:4096
	ds_read_b128 v[218:221], v141 offset:5120
	ds_read_b128 v[222:225], v141 offset:6144
	ds_read_b128 v[226:229], v141 offset:7168
	global_load_lds_dwordx4 v[142:143], off
	v_lshl_add_u64 v[142:143], s[14:15], 0, v[136:137]
	s_add_i32 m0, s9, 0xe000
	s_nop 0
	global_load_lds_dwordx4 v[142:143], off
	s_waitcnt vmcnt(8) lgkmcnt(0)
	s_barrier
	s_setprio 1
	v_mfma_f32_16x16x32_bf16 v[20:23], v[146:149], v[198:201], v[20:23]
	v_mfma_f32_16x16x32_bf16 v[28:31], v[154:157], v[198:201], v[28:31]
	v_mfma_f32_16x16x32_bf16 v[12:15], v[146:149], v[206:209], v[12:15]
	v_mfma_f32_16x16x32_bf16 v[24:27], v[154:157], v[206:209], v[24:27]
	v_mfma_f32_16x16x32_bf16 v[4:7], v[146:149], v[214:217], v[4:7]
	v_mfma_f32_16x16x32_bf16 v[16:19], v[154:157], v[214:217], v[16:19]
	v_mfma_f32_16x16x32_bf16 v[0:3], v[146:149], v[222:225], v[0:3]
	v_mfma_f32_16x16x32_bf16 v[8:11], v[154:157], v[222:225], v[8:11]
	v_mfma_f32_16x16x32_bf16 v[20:23], v[150:153], v[202:205], v[20:23]
	v_mfma_f32_16x16x32_bf16 v[28:31], v[158:161], v[202:205], v[28:31]
	v_mfma_f32_16x16x32_bf16 v[12:15], v[150:153], v[210:213], v[12:15]
	v_mfma_f32_16x16x32_bf16 v[24:27], v[158:161], v[210:213], v[24:27]
	v_mfma_f32_16x16x32_bf16 v[4:7], v[150:153], v[218:221], v[4:7]
	v_mfma_f32_16x16x32_bf16 v[16:19], v[158:161], v[218:221], v[16:19]
	v_mfma_f32_16x16x32_bf16 v[0:3], v[150:153], v[226:229], v[0:3]
	v_mfma_f32_16x16x32_bf16 v[8:11], v[158:161], v[226:229], v[8:11]
	v_mfma_f32_16x16x32_bf16 v[84:87], v[162:165], v[198:201], v[84:87]
	v_mfma_f32_16x16x32_bf16 v[92:95], v[170:173], v[198:201], v[92:95]
	v_mfma_f32_16x16x32_bf16 v[72:75], v[162:165], v[206:209], v[72:75]
	v_mfma_f32_16x16x32_bf16 v[88:91], v[170:173], v[206:209], v[88:91]
	v_mfma_f32_16x16x32_bf16 v[60:63], v[162:165], v[214:217], v[60:63]
	v_mfma_f32_16x16x32_bf16 v[80:83], v[170:173], v[214:217], v[80:83]
	v_mfma_f32_16x16x32_bf16 v[48:51], v[162:165], v[222:225], v[48:51]
	v_mfma_f32_16x16x32_bf16 v[68:71], v[170:173], v[222:225], v[68:71]
	v_mfma_f32_16x16x32_bf16 v[84:87], v[166:169], v[202:205], v[84:87]
	v_mfma_f32_16x16x32_bf16 v[92:95], v[174:177], v[202:205], v[92:95]
	v_mfma_f32_16x16x32_bf16 v[72:75], v[166:169], v[210:213], v[72:75]
	v_mfma_f32_16x16x32_bf16 v[88:91], v[174:177], v[210:213], v[88:91]
	v_mfma_f32_16x16x32_bf16 v[60:63], v[166:169], v[218:221], v[60:63]
	v_mfma_f32_16x16x32_bf16 v[80:83], v[174:177], v[218:221], v[80:83]
	v_mfma_f32_16x16x32_bf16 v[48:51], v[166:169], v[226:229], v[48:51]
	v_mfma_f32_16x16x32_bf16 v[68:71], v[174:177], v[226:229], v[68:71]
	s_setprio 0
	s_barrier
	s_add_i32 s30, s30, s34
	v_lshl_add_u64 v[142:143], s[16:17], 0, v[128:129]
	s_mov_b32 m0, s30
	ds_read_b128 v[198:201], v141 offset:16384
	ds_read_b128 v[202:205], v141 offset:17408
	ds_read_b128 v[206:209], v141 offset:18432
	ds_read_b128 v[210:213], v141 offset:19456
	ds_read_b128 v[214:217], v141 offset:20480
	ds_read_b128 v[218:221], v141 offset:21504
	ds_read_b128 v[222:225], v141 offset:22528
	ds_read_b128 v[226:229], v141 offset:23552
	global_load_lds_dwordx4 v[142:143], off
	s_add_i32 m0, s30, 0x2000
	s_add_u32 s30, s16, 0x40000
	v_lshl_add_u64 v[238:239], s[16:17], 0, v[130:131]
	s_addc_u32 s31, s17, 0
	s_add_i32 s49, s49, s34
	global_load_lds_dwordx4 v[238:239], off
	v_lshl_add_u64 v[240:241], s[30:31], 0, v[128:129]
	s_mov_b32 m0, s49
	v_lshl_add_u64 v[242:243], s[26:27], 0, v[132:133]
	global_load_lds_dwordx4 v[240:241], off
	v_lshl_add_u64 v[240:241], s[30:31], 0, v[130:131]
	s_add_i32 m0, s49, 0x2000
	s_nop 0
	global_load_lds_dwordx4 v[240:241], off
	v_lshl_add_u64 v[240:241], s[26:27], 0, v[134:135]
	s_mov_b32 m0, s9
	s_nop 0
	global_load_lds_dwordx4 v[240:241], off
	s_mov_b32 m0, s36
	s_nop 0
	global_load_lds_dwordx4 v[242:243], off
	s_waitcnt vmcnt(8) lgkmcnt(0)
	s_barrier
	s_setprio 1
	v_mfma_f32_16x16x32_bf16 v[56:59], v[146:149], v[198:201], v[56:59]
	v_mfma_f32_16x16x32_bf16 v[76:79], v[154:157], v[198:201], v[76:79]
	v_mfma_f32_16x16x32_bf16 v[44:47], v[146:149], v[206:209], v[44:47]
	v_mfma_f32_16x16x32_bf16 v[64:67], v[154:157], v[206:209], v[64:67]
	v_mfma_f32_16x16x32_bf16 v[36:39], v[146:149], v[214:217], v[36:39]
	v_mfma_f32_16x16x32_bf16 v[52:55], v[154:157], v[214:217], v[52:55]
	v_mfma_f32_16x16x32_bf16 v[32:35], v[146:149], v[222:225], v[32:35]
	v_mfma_f32_16x16x32_bf16 v[40:43], v[154:157], v[222:225], v[40:43]
	v_mfma_f32_16x16x32_bf16 v[56:59], v[150:153], v[202:205], v[56:59]
	v_mfma_f32_16x16x32_bf16 v[76:79], v[158:161], v[202:205], v[76:79]
	v_mfma_f32_16x16x32_bf16 v[44:47], v[150:153], v[210:213], v[44:47]
	v_mfma_f32_16x16x32_bf16 v[64:67], v[158:161], v[210:213], v[64:67]
	v_mfma_f32_16x16x32_bf16 v[36:39], v[150:153], v[218:221], v[36:39]
	v_mfma_f32_16x16x32_bf16 v[52:55], v[158:161], v[218:221], v[52:55]
	v_mfma_f32_16x16x32_bf16 v[32:35], v[150:153], v[226:229], v[32:35]
	v_mfma_f32_16x16x32_bf16 v[40:43], v[158:161], v[226:229], v[40:43]
	v_mfma_f32_16x16x32_bf16 v[112:115], v[162:165], v[198:201], v[112:115]
	v_mfma_f32_16x16x32_bf16 v[120:123], v[170:173], v[198:201], v[120:123]
	v_mfma_f32_16x16x32_bf16 v[104:107], v[162:165], v[206:209], v[104:107]
	v_mfma_f32_16x16x32_bf16 v[116:119], v[170:173], v[206:209], v[116:119]
	v_mfma_f32_16x16x32_bf16 v[100:103], v[162:165], v[214:217], v[100:103]
	v_mfma_f32_16x16x32_bf16 v[108:111], v[170:173], v[214:217], v[108:111]
	v_mfma_f32_16x16x32_bf16 v[96:99], v[162:165], v[222:225], v[96:99]
	v_mfma_f32_16x16x32_bf16 v[124:127], v[170:173], v[222:225], v[124:127]
	v_mfma_f32_16x16x32_bf16 v[112:115], v[166:169], v[202:205], v[112:115]
	v_mfma_f32_16x16x32_bf16 v[120:123], v[174:177], v[202:205], v[120:123]
	v_mfma_f32_16x16x32_bf16 v[104:107], v[166:169], v[210:213], v[104:107]
	v_mfma_f32_16x16x32_bf16 v[116:119], v[174:177], v[210:213], v[116:119]
	v_mfma_f32_16x16x32_bf16 v[100:103], v[166:169], v[218:221], v[100:103]
	v_mfma_f32_16x16x32_bf16 v[108:111], v[174:177], v[218:221], v[108:111]
	v_mfma_f32_16x16x32_bf16 v[96:99], v[166:169], v[226:229], v[96:99]
	v_mfma_f32_16x16x32_bf16 v[124:127], v[174:177], v[226:229], v[124:127]
	s_setprio 0
	s_barrier
	s_add_i32 s30, 0, 0x18000
	s_add_i32 s31, 0, 0x1c000
	v_add_u32_e32 v158, s30, v145
	v_add_u32_e32 v174, s31, v145
	ds_read_b128 v[146:149], v158
	ds_read_b128 v[150:153], v158 offset:1024
	ds_read_b128 v[154:157], v158 offset:2048
	ds_read_b128 v[158:161], v158 offset:3072
	ds_read_b128 v[162:165], v174
	ds_read_b128 v[166:169], v174 offset:1024
	ds_read_b128 v[170:173], v174 offset:2048
	ds_read_b128 v[174:177], v174 offset:3072
	s_add_u32 s26, s26, 0x40000
	s_addc_u32 s27, s27, 0
	s_mov_b32 m0, s37
	v_lshl_add_u64 v[244:245], s[26:27], 0, v[134:135]
	ds_read_b128 v[198:201], v141 offset:32768
	ds_read_b128 v[202:205], v141 offset:33792
	ds_read_b128 v[206:209], v141 offset:34816
	ds_read_b128 v[210:213], v141 offset:35840
	ds_read_b128 v[214:217], v141 offset:36864
	ds_read_b128 v[218:221], v141 offset:37888
	ds_read_b128 v[222:225], v141 offset:38912
	ds_read_b128 v[226:229], v141 offset:39936
	global_load_lds_dwordx4 v[244:245], off
	v_lshl_add_u64 v[244:245], s[26:27], 0, v[132:133]
	s_mov_b32 m0, s38
	s_nop 0
	global_load_lds_dwordx4 v[244:245], off
	s_waitcnt vmcnt(8) lgkmcnt(0)
	s_barrier
	s_setprio 1
	v_mfma_f32_16x16x32_bf16 v[20:23], v[146:149], v[198:201], v[20:23]
	v_mfma_f32_16x16x32_bf16 v[28:31], v[154:157], v[198:201], v[28:31]
	v_mfma_f32_16x16x32_bf16 v[12:15], v[146:149], v[206:209], v[12:15]
	v_mfma_f32_16x16x32_bf16 v[24:27], v[154:157], v[206:209], v[24:27]
	v_mfma_f32_16x16x32_bf16 v[4:7], v[146:149], v[214:217], v[4:7]
	v_mfma_f32_16x16x32_bf16 v[16:19], v[154:157], v[214:217], v[16:19]
	v_mfma_f32_16x16x32_bf16 v[0:3], v[146:149], v[222:225], v[0:3]
	v_mfma_f32_16x16x32_bf16 v[8:11], v[154:157], v[222:225], v[8:11]
	v_mfma_f32_16x16x32_bf16 v[20:23], v[150:153], v[202:205], v[20:23]
	v_mfma_f32_16x16x32_bf16 v[28:31], v[158:161], v[202:205], v[28:31]
	v_mfma_f32_16x16x32_bf16 v[12:15], v[150:153], v[210:213], v[12:15]
	v_mfma_f32_16x16x32_bf16 v[24:27], v[158:161], v[210:213], v[24:27]
	v_mfma_f32_16x16x32_bf16 v[4:7], v[150:153], v[218:221], v[4:7]
	v_mfma_f32_16x16x32_bf16 v[16:19], v[158:161], v[218:221], v[16:19]
	v_mfma_f32_16x16x32_bf16 v[0:3], v[150:153], v[226:229], v[0:3]
	v_mfma_f32_16x16x32_bf16 v[8:11], v[158:161], v[226:229], v[8:11]
	v_mfma_f32_16x16x32_bf16 v[84:87], v[162:165], v[198:201], v[84:87]
	v_mfma_f32_16x16x32_bf16 v[92:95], v[170:173], v[198:201], v[92:95]
	v_mfma_f32_16x16x32_bf16 v[72:75], v[162:165], v[206:209], v[72:75]
	v_mfma_f32_16x16x32_bf16 v[88:91], v[170:173], v[206:209], v[88:91]
	v_mfma_f32_16x16x32_bf16 v[60:63], v[162:165], v[214:217], v[60:63]
	v_mfma_f32_16x16x32_bf16 v[80:83], v[170:173], v[214:217], v[80:83]
	v_mfma_f32_16x16x32_bf16 v[48:51], v[162:165], v[222:225], v[48:51]
	v_mfma_f32_16x16x32_bf16 v[68:71], v[170:173], v[222:225], v[68:71]
	v_mfma_f32_16x16x32_bf16 v[84:87], v[166:169], v[202:205], v[84:87]
	v_mfma_f32_16x16x32_bf16 v[92:95], v[174:177], v[202:205], v[92:95]
	v_mfma_f32_16x16x32_bf16 v[72:75], v[166:169], v[210:213], v[72:75]
	v_mfma_f32_16x16x32_bf16 v[88:91], v[174:177], v[210:213], v[88:91]
	v_mfma_f32_16x16x32_bf16 v[60:63], v[166:169], v[218:221], v[60:63]
	v_mfma_f32_16x16x32_bf16 v[80:83], v[174:177], v[218:221], v[80:83]
	v_mfma_f32_16x16x32_bf16 v[48:51], v[166:169], v[226:229], v[48:51]
	v_mfma_f32_16x16x32_bf16 v[68:71], v[174:177], v[226:229], v[68:71]
	s_setprio 0
	s_barrier
	s_add_i32 s26, s30, s34
	v_lshl_add_u64 v[142:143], v[142:143], 0, s[90:91]
	s_mov_b32 m0, s26
	ds_read_b128 v[198:201], v141 offset:49152
	ds_read_b128 v[202:205], v141 offset:50176
	ds_read_b128 v[206:209], v141 offset:51200
	ds_read_b128 v[210:213], v141 offset:52224
	ds_read_b128 v[214:217], v141 offset:53248
	ds_read_b128 v[218:221], v141 offset:54272
	ds_read_b128 v[222:225], v141 offset:55296
	ds_read_b128 v[226:229], v141 offset:56320
	global_load_lds_dwordx4 v[142:143], off
	s_add_i32 m0, s26, 0x2000
	s_add_u32 s16, s16, 0x40080
	v_lshl_add_u64 v[142:143], v[238:239], 0, s[90:91]
	s_addc_u32 s17, s17, 0
	s_add_i32 s26, s31, s34
	global_load_lds_dwordx4 v[142:143], off
	v_lshl_add_u64 v[142:143], s[16:17], 0, v[128:129]
	s_mov_b32 m0, s26
	s_nop 0
	global_load_lds_dwordx4 v[142:143], off
	v_lshl_add_u64 v[142:143], s[16:17], 0, v[130:131]
	s_add_i32 m0, s26, 0x2000
	s_nop 0
	global_load_lds_dwordx4 v[142:143], off
	v_lshl_add_u64 v[142:143], v[240:241], 0, s[90:91]
	s_mov_b32 m0, s40
	s_nop 0
	global_load_lds_dwordx4 v[142:143], off
	v_lshl_add_u64 v[142:143], v[242:243], 0, s[90:91]
	s_mov_b32 m0, s41
	s_nop 0
	global_load_lds_dwordx4 v[142:143], off
	s_waitcnt vmcnt(8) lgkmcnt(0)
	s_barrier
	s_setprio 1
	v_mfma_f32_16x16x32_bf16 v[56:59], v[146:149], v[198:201], v[56:59]
	v_mfma_f32_16x16x32_bf16 v[76:79], v[154:157], v[198:201], v[76:79]
	v_mfma_f32_16x16x32_bf16 v[44:47], v[146:149], v[206:209], v[44:47]
	v_mfma_f32_16x16x32_bf16 v[64:67], v[154:157], v[206:209], v[64:67]
	v_mfma_f32_16x16x32_bf16 v[36:39], v[146:149], v[214:217], v[36:39]
	v_mfma_f32_16x16x32_bf16 v[52:55], v[154:157], v[214:217], v[52:55]
	v_mfma_f32_16x16x32_bf16 v[32:35], v[146:149], v[222:225], v[32:35]
	v_mfma_f32_16x16x32_bf16 v[40:43], v[154:157], v[222:225], v[40:43]
	v_mfma_f32_16x16x32_bf16 v[56:59], v[150:153], v[202:205], v[56:59]
	v_mfma_f32_16x16x32_bf16 v[76:79], v[158:161], v[202:205], v[76:79]
	v_mfma_f32_16x16x32_bf16 v[44:47], v[150:153], v[210:213], v[44:47]
	v_mfma_f32_16x16x32_bf16 v[64:67], v[158:161], v[210:213], v[64:67]
	v_mfma_f32_16x16x32_bf16 v[36:39], v[150:153], v[218:221], v[36:39]
	v_mfma_f32_16x16x32_bf16 v[52:55], v[158:161], v[218:221], v[52:55]
	v_mfma_f32_16x16x32_bf16 v[32:35], v[150:153], v[226:229], v[32:35]
	v_mfma_f32_16x16x32_bf16 v[40:43], v[158:161], v[226:229], v[40:43]
	v_mfma_f32_16x16x32_bf16 v[112:115], v[162:165], v[198:201], v[112:115]
	v_mfma_f32_16x16x32_bf16 v[120:123], v[170:173], v[198:201], v[120:123]
	v_mfma_f32_16x16x32_bf16 v[104:107], v[162:165], v[206:209], v[104:107]
	v_mfma_f32_16x16x32_bf16 v[116:119], v[170:173], v[206:209], v[116:119]
	v_mfma_f32_16x16x32_bf16 v[100:103], v[162:165], v[214:217], v[100:103]
	v_mfma_f32_16x16x32_bf16 v[108:111], v[170:173], v[214:217], v[108:111]
	v_mfma_f32_16x16x32_bf16 v[96:99], v[162:165], v[222:225], v[96:99]
	v_mfma_f32_16x16x32_bf16 v[124:127], v[170:173], v[222:225], v[124:127]
	v_mfma_f32_16x16x32_bf16 v[112:115], v[166:169], v[202:205], v[112:115]
	v_mfma_f32_16x16x32_bf16 v[120:123], v[174:177], v[202:205], v[120:123]
	v_mfma_f32_16x16x32_bf16 v[104:107], v[166:169], v[210:213], v[104:107]
	v_mfma_f32_16x16x32_bf16 v[116:119], v[174:177], v[210:213], v[116:119]
	v_mfma_f32_16x16x32_bf16 v[100:103], v[166:169], v[218:221], v[100:103]
	v_mfma_f32_16x16x32_bf16 v[108:111], v[174:177], v[218:221], v[108:111]
	v_mfma_f32_16x16x32_bf16 v[96:99], v[166:169], v[226:229], v[96:99]
	v_mfma_f32_16x16x32_bf16 v[124:127], v[174:177], v[226:229], v[124:127]
	s_setprio 0
	s_barrier
	s_add_i32 s48, s48, 2
	s_add_u32 s46, s46, 0x100
	s_addc_u32 s47, s47, 0
	s_add_u32 s14, s14, 0x100
	s_addc_u32 s15, s15, 0
	s_cmp_gt_u32 s48, 13
	s_cbranch_scc0 .LBB0_395
	s_and_b64 vcc, exec, s[12:13]
	s_cbranch_vccz .LBB0_398
	s_barrier

.LBB0_451:
	s_add_i32 s60, s50, 2
	s_add_u32 s30, s8, 0x80
	s_addc_u32 s31, s9, 0
	s_add_i32 s61, 0, 0x10000
	s_cmp_eq_u32 s21, s50
	s_cselect_b32 s51, s47, s31
	s_cselect_b32 s50, s46, s30
	v_add_u32_e32 v128, s61, v173
	s_cselect_b32 s31, s49, vcc_lo
	s_cselect_b32 s30, s48, s45
	s_add_i32 vcc_hi, 0, 0x14000
	ds_read_b128 v[130:133], v128
	ds_read_b128 v[134:137], v128 offset:1024
	ds_read_b128 v[138:141], v128 offset:2048
	ds_read_b128 v[142:145], v128 offset:3072
	v_add_u32_e32 v128, vcc_hi, v173
	ds_read_b128 v[158:161], v128
	ds_read_b128 v[162:165], v128 offset:1024
	ds_read_b128 v[166:169], v128 offset:2048
	ds_read_b128 v[198:201], v128 offset:3072
	v_lshl_add_u64 v[170:171], s[8:9], 0, v[156:157]
	s_add_i32 m0, s85, 0xc000
	ds_read_b128 v[202:205], v190
	ds_read_b128 v[206:209], v190 offset:1024
	ds_read_b128 v[210:213], v190 offset:2048
	ds_read_b128 v[214:217], v190 offset:3072
	ds_read_b128 v[218:221], v190 offset:4096
	ds_read_b128 v[222:225], v190 offset:5120
	ds_read_b128 v[226:229], v190 offset:6144
	ds_read_b128 v[238:241], v190 offset:7168
	global_load_lds_dwordx4 v[170:171], off
	v_lshl_add_u64 v[170:171], s[8:9], 0, v[154:155]
	s_add_i32 m0, s85, 0xe000
	s_nop 0
	global_load_lds_dwordx4 v[170:171], off
	s_waitcnt vmcnt(8) lgkmcnt(0)
	s_barrier
	s_setprio 1
	v_mfma_f32_16x16x32_bf16 v[124:127], v[130:133], v[202:205], v[124:127]
	v_mfma_f32_16x16x32_bf16 v[120:123], v[138:141], v[202:205], v[120:123]
	v_mfma_f32_16x16x32_bf16 v[108:111], v[130:133], v[210:213], v[108:111]
	v_mfma_f32_16x16x32_bf16 v[104:107], v[138:141], v[210:213], v[104:107]
	v_mfma_f32_16x16x32_bf16 v[92:95], v[130:133], v[218:221], v[92:95]
	v_mfma_f32_16x16x32_bf16 v[88:91], v[138:141], v[218:221], v[88:91]
	v_mfma_f32_16x16x32_bf16 v[76:79], v[130:133], v[226:229], v[76:79]
	v_mfma_f32_16x16x32_bf16 v[72:75], v[138:141], v[226:229], v[72:75]
	v_mfma_f32_16x16x32_bf16 v[124:127], v[134:137], v[206:209], v[124:127]
	v_mfma_f32_16x16x32_bf16 v[120:123], v[142:145], v[206:209], v[120:123]
	v_mfma_f32_16x16x32_bf16 v[108:111], v[134:137], v[214:217], v[108:111]
	v_mfma_f32_16x16x32_bf16 v[104:107], v[142:145], v[214:217], v[104:107]
	v_mfma_f32_16x16x32_bf16 v[92:95], v[134:137], v[222:225], v[92:95]
	v_mfma_f32_16x16x32_bf16 v[88:91], v[142:145], v[222:225], v[88:91]
	v_mfma_f32_16x16x32_bf16 v[76:79], v[134:137], v[238:241], v[76:79]
	v_mfma_f32_16x16x32_bf16 v[72:75], v[142:145], v[238:241], v[72:75]
	v_mfma_f32_16x16x32_bf16 v[116:119], v[158:161], v[202:205], v[116:119]
	v_mfma_f32_16x16x32_bf16 v[112:115], v[166:169], v[202:205], v[112:115]
	v_mfma_f32_16x16x32_bf16 v[100:103], v[158:161], v[210:213], v[100:103]
	v_mfma_f32_16x16x32_bf16 v[96:99], v[166:169], v[210:213], v[96:99]
	v_mfma_f32_16x16x32_bf16 v[84:87], v[158:161], v[218:221], v[84:87]
	v_mfma_f32_16x16x32_bf16 v[80:83], v[166:169], v[218:221], v[80:83]
	v_mfma_f32_16x16x32_bf16 v[68:71], v[158:161], v[226:229], v[68:71]
	v_mfma_f32_16x16x32_bf16 v[64:67], v[166:169], v[226:229], v[64:67]
	v_mfma_f32_16x16x32_bf16 v[116:119], v[162:165], v[206:209], v[116:119]
	v_mfma_f32_16x16x32_bf16 v[112:115], v[198:201], v[206:209], v[112:115]
	v_mfma_f32_16x16x32_bf16 v[100:103], v[162:165], v[214:217], v[100:103]
	v_mfma_f32_16x16x32_bf16 v[96:99], v[198:201], v[214:217], v[96:99]
	v_mfma_f32_16x16x32_bf16 v[84:87], v[162:165], v[222:225], v[84:87]
	v_mfma_f32_16x16x32_bf16 v[80:83], v[198:201], v[222:225], v[80:83]
	v_mfma_f32_16x16x32_bf16 v[68:71], v[162:165], v[238:241], v[68:71]
	v_mfma_f32_16x16x32_bf16 v[64:67], v[198:201], v[238:241], v[64:67]
	s_setprio 0
	s_barrier
	s_add_i32 s61, s61, s82
	v_lshl_add_u64 v[170:171], s[30:31], 0, v[148:149]
	s_mov_b32 m0, s61
	ds_read_b128 v[202:205], v190 offset:16384
	ds_read_b128 v[206:209], v190 offset:17408
	ds_read_b128 v[210:213], v190 offset:18432
	ds_read_b128 v[214:217], v190 offset:19456
	ds_read_b128 v[218:221], v190 offset:20480
	ds_read_b128 v[222:225], v190 offset:21504
	ds_read_b128 v[226:229], v190 offset:22528
	ds_read_b128 v[238:241], v190 offset:23552
	global_load_lds_dwordx4 v[170:171], off
	s_add_i32 m0, s61, 0x2000
	v_lshl_add_u64 v[242:243], s[30:31], 0, v[152:153]
	s_add_u32 s30, s30, s96
	s_addc_u32 s31, s31, 0
	s_add_i32 s61, vcc_hi, s82
	global_load_lds_dwordx4 v[242:243], off
	v_lshl_add_u64 v[244:245], s[30:31], 0, v[148:149]
	s_mov_b32 m0, s61
	v_lshl_add_u64 v[246:247], s[30:31], 0, v[152:153]
	global_load_lds_dwordx4 v[244:245], off
	s_add_i32 m0, s61, 0x2000
	v_lshl_add_u64 v[248:249], s[50:51], 0, v[146:147]
	global_load_lds_dwordx4 v[246:247], off
	s_mov_b32 m0, s85
	v_lshl_add_u64 v[250:251], s[50:51], 0, v[150:151]
	global_load_lds_dwordx4 v[248:249], off
	s_mov_b32 m0, s86
	s_nop 0
	global_load_lds_dwordx4 v[250:251], off
	s_waitcnt vmcnt(8) lgkmcnt(0)
	s_barrier
	s_setprio 1
	v_mfma_f32_16x16x32_bf16 v[60:63], v[130:133], v[202:205], v[60:63]
	v_mfma_f32_16x16x32_bf16 v[56:59], v[138:141], v[202:205], v[56:59]
	v_mfma_f32_16x16x32_bf16 v[44:47], v[130:133], v[210:213], v[44:47]
	v_mfma_f32_16x16x32_bf16 v[40:43], v[138:141], v[210:213], v[40:43]
	v_mfma_f32_16x16x32_bf16 v[28:31], v[130:133], v[218:221], v[28:31]
	v_mfma_f32_16x16x32_bf16 v[24:27], v[138:141], v[218:221], v[24:27]
	v_mfma_f32_16x16x32_bf16 v[12:15], v[130:133], v[226:229], v[12:15]
	v_mfma_f32_16x16x32_bf16 v[8:11], v[138:141], v[226:229], v[8:11]
	v_mfma_f32_16x16x32_bf16 v[60:63], v[134:137], v[206:209], v[60:63]
	v_mfma_f32_16x16x32_bf16 v[56:59], v[142:145], v[206:209], v[56:59]
	v_mfma_f32_16x16x32_bf16 v[44:47], v[134:137], v[214:217], v[44:47]
	v_mfma_f32_16x16x32_bf16 v[40:43], v[142:145], v[214:217], v[40:43]
	v_mfma_f32_16x16x32_bf16 v[28:31], v[134:137], v[222:225], v[28:31]
	v_mfma_f32_16x16x32_bf16 v[24:27], v[142:145], v[222:225], v[24:27]
	v_mfma_f32_16x16x32_bf16 v[12:15], v[134:137], v[238:241], v[12:15]
	v_mfma_f32_16x16x32_bf16 v[8:11], v[142:145], v[238:241], v[8:11]
	v_mfma_f32_16x16x32_bf16 v[52:55], v[158:161], v[202:205], v[52:55]
	v_mfma_f32_16x16x32_bf16 v[48:51], v[166:169], v[202:205], v[48:51]
	v_mfma_f32_16x16x32_bf16 v[36:39], v[158:161], v[210:213], v[36:39]
	v_mfma_f32_16x16x32_bf16 v[32:35], v[166:169], v[210:213], v[32:35]
	v_mfma_f32_16x16x32_bf16 v[20:23], v[158:161], v[218:221], v[20:23]
	v_mfma_f32_16x16x32_bf16 v[16:19], v[166:169], v[218:221], v[16:19]
	v_mfma_f32_16x16x32_bf16 v[4:7], v[158:161], v[226:229], v[4:7]
	v_mfma_f32_16x16x32_bf16 v[0:3], v[166:169], v[226:229], v[0:3]
	v_mfma_f32_16x16x32_bf16 v[52:55], v[162:165], v[206:209], v[52:55]
	v_mfma_f32_16x16x32_bf16 v[48:51], v[198:201], v[206:209], v[48:51]
	v_mfma_f32_16x16x32_bf16 v[36:39], v[162:165], v[214:217], v[36:39]
	v_mfma_f32_16x16x32_bf16 v[32:35], v[198:201], v[214:217], v[32:35]
	v_mfma_f32_16x16x32_bf16 v[20:23], v[162:165], v[222:225], v[20:23]
	v_mfma_f32_16x16x32_bf16 v[16:19], v[198:201], v[222:225], v[16:19]
	v_mfma_f32_16x16x32_bf16 v[4:7], v[162:165], v[238:241], v[4:7]
	v_mfma_f32_16x16x32_bf16 v[0:3], v[198:201], v[238:241], v[0:3]
	s_setprio 0
	s_barrier
	s_add_i32 s61, 0, 0x18000
	v_add_u32_e32 v128, s61, v173
	s_add_i32 vcc_hi, 0, 0x1c000
	ds_read_b128 v[130:133], v128
	ds_read_b128 v[134:137], v128 offset:1024
	ds_read_b128 v[138:141], v128 offset:2048
	ds_read_b128 v[142:145], v128 offset:3072
	v_add_u32_e32 v128, vcc_hi, v173
	ds_read_b128 v[158:161], v128
	ds_read_b128 v[162:165], v128 offset:1024
	ds_read_b128 v[166:169], v128 offset:2048
	ds_read_b128 v[198:201], v128 offset:3072
	s_add_u32 s30, s50, s96
	s_addc_u32 s31, s51, 0
	s_mov_b32 m0, s87
	v_lshl_add_u64 v[252:253], s[30:31], 0, v[146:147]
	ds_read_b128 v[202:205], v190 offset:32768
	ds_read_b128 v[206:209], v190 offset:33792
	ds_read_b128 v[210:213], v190 offset:34816
	ds_read_b128 v[214:217], v190 offset:35840
	ds_read_b128 v[218:221], v190 offset:36864
	ds_read_b128 v[222:225], v190 offset:37888
	ds_read_b128 v[226:229], v190 offset:38912
	ds_read_b128 v[238:241], v190 offset:39936
	global_load_lds_dwordx4 v[252:253], off
	v_lshl_add_u64 v[252:253], s[30:31], 0, v[150:151]
	s_mov_b32 m0, s88
	s_nop 0
	global_load_lds_dwordx4 v[252:253], off
	s_waitcnt vmcnt(8) lgkmcnt(0)
	s_barrier
	s_setprio 1
	v_mfma_f32_16x16x32_bf16 v[124:127], v[130:133], v[202:205], v[124:127]
	v_mfma_f32_16x16x32_bf16 v[120:123], v[138:141], v[202:205], v[120:123]
	v_mfma_f32_16x16x32_bf16 v[108:111], v[130:133], v[210:213], v[108:111]
	v_mfma_f32_16x16x32_bf16 v[104:107], v[138:141], v[210:213], v[104:107]
	v_mfma_f32_16x16x32_bf16 v[92:95], v[130:133], v[218:221], v[92:95]
	v_mfma_f32_16x16x32_bf16 v[88:91], v[138:141], v[218:221], v[88:91]
	v_mfma_f32_16x16x32_bf16 v[76:79], v[130:133], v[226:229], v[76:79]
	v_mfma_f32_16x16x32_bf16 v[72:75], v[138:141], v[226:229], v[72:75]
	v_mfma_f32_16x16x32_bf16 v[124:127], v[134:137], v[206:209], v[124:127]
	v_mfma_f32_16x16x32_bf16 v[120:123], v[142:145], v[206:209], v[120:123]
	v_mfma_f32_16x16x32_bf16 v[108:111], v[134:137], v[214:217], v[108:111]
	v_mfma_f32_16x16x32_bf16 v[104:107], v[142:145], v[214:217], v[104:107]
	v_mfma_f32_16x16x32_bf16 v[92:95], v[134:137], v[222:225], v[92:95]
	v_mfma_f32_16x16x32_bf16 v[88:91], v[142:145], v[222:225], v[88:91]
	v_mfma_f32_16x16x32_bf16 v[76:79], v[134:137], v[238:241], v[76:79]
	v_mfma_f32_16x16x32_bf16 v[72:75], v[142:145], v[238:241], v[72:75]
	v_mfma_f32_16x16x32_bf16 v[116:119], v[158:161], v[202:205], v[116:119]
	v_mfma_f32_16x16x32_bf16 v[112:115], v[166:169], v[202:205], v[112:115]
	v_mfma_f32_16x16x32_bf16 v[100:103], v[158:161], v[210:213], v[100:103]
	v_mfma_f32_16x16x32_bf16 v[96:99], v[166:169], v[210:213], v[96:99]
	v_mfma_f32_16x16x32_bf16 v[84:87], v[158:161], v[218:221], v[84:87]
	v_mfma_f32_16x16x32_bf16 v[80:83], v[166:169], v[218:221], v[80:83]
	v_mfma_f32_16x16x32_bf16 v[68:71], v[158:161], v[226:229], v[68:71]
	v_mfma_f32_16x16x32_bf16 v[64:67], v[166:169], v[226:229], v[64:67]
	v_mfma_f32_16x16x32_bf16 v[116:119], v[162:165], v[206:209], v[116:119]
	v_mfma_f32_16x16x32_bf16 v[112:115], v[198:201], v[206:209], v[112:115]
	v_mfma_f32_16x16x32_bf16 v[100:103], v[162:165], v[214:217], v[100:103]
	v_mfma_f32_16x16x32_bf16 v[96:99], v[198:201], v[214:217], v[96:99]
	v_mfma_f32_16x16x32_bf16 v[84:87], v[162:165], v[222:225], v[84:87]
	v_mfma_f32_16x16x32_bf16 v[80:83], v[198:201], v[222:225], v[80:83]
	v_mfma_f32_16x16x32_bf16 v[68:71], v[162:165], v[238:241], v[68:71]
	v_mfma_f32_16x16x32_bf16 v[64:67], v[198:201], v[238:241], v[64:67]
	s_setprio 0
	s_barrier
	s_add_i32 s30, s61, s82
	v_lshl_add_u64 v[170:171], v[170:171], 0, s[90:91]
	s_mov_b32 m0, s30
	ds_read_b128 v[202:205], v190 offset:49152
	ds_read_b128 v[206:209], v190 offset:50176
	ds_read_b128 v[210:213], v190 offset:51200
	ds_read_b128 v[214:217], v190 offset:52224
	ds_read_b128 v[218:221], v190 offset:53248
	ds_read_b128 v[222:225], v190 offset:54272
	ds_read_b128 v[226:229], v190 offset:55296
	ds_read_b128 v[238:241], v190 offset:56320
	global_load_lds_dwordx4 v[170:171], off
	v_lshl_add_u64 v[170:171], v[242:243], 0, s[90:91]
	s_add_i32 m0, s30, 0x2000
	s_add_i32 s30, vcc_hi, s82
	global_load_lds_dwordx4 v[170:171], off
	v_lshl_add_u64 v[170:171], v[244:245], 0, s[90:91]
	s_mov_b32 m0, s30
	s_nop 0
	global_load_lds_dwordx4 v[170:171], off
	v_lshl_add_u64 v[170:171], v[246:247], 0, s[90:91]
	s_add_i32 m0, s30, 0x2000
	s_nop 0
	global_load_lds_dwordx4 v[170:171], off
	v_lshl_add_u64 v[170:171], v[248:249], 0, s[90:91]
	s_mov_b32 m0, s53
	s_nop 0
	global_load_lds_dwordx4 v[170:171], off
	v_lshl_add_u64 v[170:171], v[250:251], 0, s[90:91]
	s_mov_b32 m0, s92
	s_nop 0
	global_load_lds_dwordx4 v[170:171], off
	s_waitcnt vmcnt(8) lgkmcnt(0)
	s_barrier
	s_setprio 1
	v_mfma_f32_16x16x32_bf16 v[60:63], v[130:133], v[202:205], v[60:63]
	v_mfma_f32_16x16x32_bf16 v[56:59], v[138:141], v[202:205], v[56:59]
	v_mfma_f32_16x16x32_bf16 v[44:47], v[130:133], v[210:213], v[44:47]
	v_mfma_f32_16x16x32_bf16 v[40:43], v[138:141], v[210:213], v[40:43]
	v_mfma_f32_16x16x32_bf16 v[28:31], v[130:133], v[218:221], v[28:31]
	v_mfma_f32_16x16x32_bf16 v[24:27], v[138:141], v[218:221], v[24:27]
	v_mfma_f32_16x16x32_bf16 v[12:15], v[130:133], v[226:229], v[12:15]
	v_mfma_f32_16x16x32_bf16 v[8:11], v[138:141], v[226:229], v[8:11]
	v_mfma_f32_16x16x32_bf16 v[60:63], v[134:137], v[206:209], v[60:63]
	v_mfma_f32_16x16x32_bf16 v[56:59], v[142:145], v[206:209], v[56:59]
	v_mfma_f32_16x16x32_bf16 v[44:47], v[134:137], v[214:217], v[44:47]
	v_mfma_f32_16x16x32_bf16 v[40:43], v[142:145], v[214:217], v[40:43]
	v_mfma_f32_16x16x32_bf16 v[28:31], v[134:137], v[222:225], v[28:31]
	v_mfma_f32_16x16x32_bf16 v[24:27], v[142:145], v[222:225], v[24:27]
	v_mfma_f32_16x16x32_bf16 v[12:15], v[134:137], v[238:241], v[12:15]
	v_mfma_f32_16x16x32_bf16 v[8:11], v[142:145], v[238:241], v[8:11]
	v_mfma_f32_16x16x32_bf16 v[52:55], v[158:161], v[202:205], v[52:55]
	v_mfma_f32_16x16x32_bf16 v[48:51], v[166:169], v[202:205], v[48:51]
	v_mfma_f32_16x16x32_bf16 v[36:39], v[158:161], v[210:213], v[36:39]
	v_mfma_f32_16x16x32_bf16 v[32:35], v[166:169], v[210:213], v[32:35]
	v_mfma_f32_16x16x32_bf16 v[20:23], v[158:161], v[218:221], v[20:23]
	v_mfma_f32_16x16x32_bf16 v[16:19], v[166:169], v[218:221], v[16:19]
	v_mfma_f32_16x16x32_bf16 v[4:7], v[158:161], v[226:229], v[4:7]
	v_mfma_f32_16x16x32_bf16 v[0:3], v[166:169], v[226:229], v[0:3]
	v_mfma_f32_16x16x32_bf16 v[52:55], v[162:165], v[206:209], v[52:55]
	v_mfma_f32_16x16x32_bf16 v[48:51], v[198:201], v[206:209], v[48:51]
	v_mfma_f32_16x16x32_bf16 v[36:39], v[162:165], v[214:217], v[36:39]
	v_mfma_f32_16x16x32_bf16 v[32:35], v[198:201], v[214:217], v[32:35]
	v_mfma_f32_16x16x32_bf16 v[20:23], v[162:165], v[222:225], v[20:23]
	v_mfma_f32_16x16x32_bf16 v[16:19], v[198:201], v[222:225], v[16:19]
	v_mfma_f32_16x16x32_bf16 v[4:7], v[162:165], v[238:241], v[4:7]
	v_mfma_f32_16x16x32_bf16 v[0:3], v[198:201], v[238:241], v[0:3]
	s_setprio 0
	s_barrier
	s_add_u32 s45, s45, 0x100
	s_addc_u32 vcc_lo, vcc_lo, 0
	s_add_u32 s8, s8, 0x100
	s_addc_u32 s9, s9, 0
	s_cmp_ge_i32 s60, s5
	s_mov_b32 s50, s60
	s_cbranch_scc0 .LBB0_451

.LBB0_638:
	s_add_u32 s26, s24, 0xfffc0080
	s_addc_u32 s27, s25, -1
	s_add_i32 s30, 0, 0x10000
	s_cmp_eq_u32 s51, 12
	s_cselect_b32 s29, s15, s27
	s_cselect_b32 s28, s21, s26
	s_cselect_b32 s27, s13, s50
	s_cselect_b32 s26, s23, s49
	s_add_i32 s31, 0, 0x14000
	v_add_u32_e32 v156, s30, v145
	v_add_u32_e32 v172, s31, v145
	ds_read_b128 v[140:143], v156
	ds_read_b128 v[148:151], v156 offset:1024
	ds_read_b128 v[152:155], v156 offset:2048
	ds_read_b128 v[156:159], v156 offset:3072
	ds_read_b128 v[160:163], v172
	ds_read_b128 v[164:167], v172 offset:1024
	ds_read_b128 v[168:171], v172 offset:2048
	ds_read_b128 v[172:175], v172 offset:3072
	v_lshl_add_u64 v[176:177], s[24:25], 0, v[138:139]
	s_add_i32 m0, s1, 0xc000
	ds_read_b128 v[198:201], v147
	ds_read_b128 v[202:205], v147 offset:1024
	ds_read_b128 v[206:209], v147 offset:2048
	ds_read_b128 v[210:213], v147 offset:3072
	ds_read_b128 v[214:217], v147 offset:4096
	ds_read_b128 v[218:221], v147 offset:5120
	ds_read_b128 v[222:225], v147 offset:6144
	ds_read_b128 v[226:229], v147 offset:7168
	global_load_lds_dwordx4 v[176:177], off
	v_lshl_add_u64 v[176:177], s[24:25], 0, v[136:137]
	s_add_i32 m0, s1, 0xe000
	s_nop 0
	global_load_lds_dwordx4 v[176:177], off
	s_waitcnt vmcnt(8) lgkmcnt(0)
	s_barrier
	s_setprio 1
	v_mfma_f32_16x16x32_bf16 v[120:123], v[140:143], v[198:201], v[120:123]
	v_mfma_f32_16x16x32_bf16 v[112:115], v[152:155], v[198:201], v[112:115]
	v_mfma_f32_16x16x32_bf16 v[104:107], v[140:143], v[206:209], v[104:107]
	v_mfma_f32_16x16x32_bf16 v[96:99], v[152:155], v[206:209], v[96:99]
	v_mfma_f32_16x16x32_bf16 v[88:91], v[140:143], v[214:217], v[88:91]
	v_mfma_f32_16x16x32_bf16 v[80:83], v[152:155], v[214:217], v[80:83]
	v_mfma_f32_16x16x32_bf16 v[72:75], v[140:143], v[222:225], v[72:75]
	v_mfma_f32_16x16x32_bf16 v[64:67], v[152:155], v[222:225], v[64:67]
	v_mfma_f32_16x16x32_bf16 v[120:123], v[148:151], v[202:205], v[120:123]
	v_mfma_f32_16x16x32_bf16 v[112:115], v[156:159], v[202:205], v[112:115]
	v_mfma_f32_16x16x32_bf16 v[104:107], v[148:151], v[210:213], v[104:107]
	v_mfma_f32_16x16x32_bf16 v[96:99], v[156:159], v[210:213], v[96:99]
	v_mfma_f32_16x16x32_bf16 v[88:91], v[148:151], v[218:221], v[88:91]
	v_mfma_f32_16x16x32_bf16 v[80:83], v[156:159], v[218:221], v[80:83]
	v_mfma_f32_16x16x32_bf16 v[72:75], v[148:151], v[226:229], v[72:75]
	v_mfma_f32_16x16x32_bf16 v[64:67], v[156:159], v[226:229], v[64:67]
	v_mfma_f32_16x16x32_bf16 v[124:127], v[160:163], v[198:201], v[124:127]
	v_mfma_f32_16x16x32_bf16 v[116:119], v[168:171], v[198:201], v[116:119]
	v_mfma_f32_16x16x32_bf16 v[108:111], v[160:163], v[206:209], v[108:111]
	v_mfma_f32_16x16x32_bf16 v[100:103], v[168:171], v[206:209], v[100:103]
	v_mfma_f32_16x16x32_bf16 v[92:95], v[160:163], v[214:217], v[92:95]
	v_mfma_f32_16x16x32_bf16 v[84:87], v[168:171], v[214:217], v[84:87]
	v_mfma_f32_16x16x32_bf16 v[76:79], v[160:163], v[222:225], v[76:79]
	v_mfma_f32_16x16x32_bf16 v[68:71], v[168:171], v[222:225], v[68:71]
	v_mfma_f32_16x16x32_bf16 v[124:127], v[164:167], v[202:205], v[124:127]
	v_mfma_f32_16x16x32_bf16 v[116:119], v[172:175], v[202:205], v[116:119]
	v_mfma_f32_16x16x32_bf16 v[108:111], v[164:167], v[210:213], v[108:111]
	v_mfma_f32_16x16x32_bf16 v[100:103], v[172:175], v[210:213], v[100:103]
	v_mfma_f32_16x16x32_bf16 v[92:95], v[164:167], v[218:221], v[92:95]
	v_mfma_f32_16x16x32_bf16 v[84:87], v[172:175], v[218:221], v[84:87]
	v_mfma_f32_16x16x32_bf16 v[76:79], v[164:167], v[226:229], v[76:79]
	v_mfma_f32_16x16x32_bf16 v[68:71], v[172:175], v[226:229], v[68:71]
	s_setprio 0
	s_barrier
	s_add_i32 s30, s30, s45
	v_lshl_add_u64 v[176:177], s[26:27], 0, v[128:129]
	s_mov_b32 m0, s30
	ds_read_b128 v[198:201], v147 offset:16384
	ds_read_b128 v[202:205], v147 offset:17408
	ds_read_b128 v[206:209], v147 offset:18432
	ds_read_b128 v[210:213], v147 offset:19456
	ds_read_b128 v[214:217], v147 offset:20480
	ds_read_b128 v[218:221], v147 offset:21504
	ds_read_b128 v[222:225], v147 offset:22528
	ds_read_b128 v[226:229], v147 offset:23552
	global_load_lds_dwordx4 v[176:177], off
	s_add_i32 m0, s30, 0x2000
	s_add_u32 s52, s26, 0x40000
	v_lshl_add_u64 v[238:239], s[26:27], 0, v[130:131]
	s_addc_u32 s53, s27, 0
	s_add_i32 s30, s31, s45
	global_load_lds_dwordx4 v[238:239], off
	v_lshl_add_u64 v[240:241], s[52:53], 0, v[128:129]
	s_mov_b32 m0, s30
	v_lshl_add_u64 v[242:243], s[28:29], 0, v[132:133]
	global_load_lds_dwordx4 v[240:241], off
	v_lshl_add_u64 v[240:241], s[52:53], 0, v[130:131]
	s_add_i32 m0, s30, 0x2000
	s_nop 0
	global_load_lds_dwordx4 v[240:241], off
	v_lshl_add_u64 v[240:241], s[28:29], 0, v[134:135]
	s_mov_b32 m0, s1
	s_nop 0
	global_load_lds_dwordx4 v[240:241], off
	s_mov_b32 m0, s43
	s_nop 0
	global_load_lds_dwordx4 v[242:243], off
	s_waitcnt vmcnt(8) lgkmcnt(0)
	s_barrier
	s_setprio 1
	v_mfma_f32_16x16x32_bf16 v[56:59], v[140:143], v[198:201], v[56:59]
	v_mfma_f32_16x16x32_bf16 v[48:51], v[152:155], v[198:201], v[48:51]
	v_mfma_f32_16x16x32_bf16 v[40:43], v[140:143], v[206:209], v[40:43]
	v_mfma_f32_16x16x32_bf16 v[32:35], v[152:155], v[206:209], v[32:35]
	v_mfma_f32_16x16x32_bf16 v[24:27], v[140:143], v[214:217], v[24:27]
	v_mfma_f32_16x16x32_bf16 v[16:19], v[152:155], v[214:217], v[16:19]
	v_mfma_f32_16x16x32_bf16 v[8:11], v[140:143], v[222:225], v[8:11]
	v_mfma_f32_16x16x32_bf16 v[0:3], v[152:155], v[222:225], v[0:3]
	v_mfma_f32_16x16x32_bf16 v[56:59], v[148:151], v[202:205], v[56:59]
	v_mfma_f32_16x16x32_bf16 v[48:51], v[156:159], v[202:205], v[48:51]
	v_mfma_f32_16x16x32_bf16 v[40:43], v[148:151], v[210:213], v[40:43]
	v_mfma_f32_16x16x32_bf16 v[32:35], v[156:159], v[210:213], v[32:35]
	v_mfma_f32_16x16x32_bf16 v[24:27], v[148:151], v[218:221], v[24:27]
	v_mfma_f32_16x16x32_bf16 v[16:19], v[156:159], v[218:221], v[16:19]
	v_mfma_f32_16x16x32_bf16 v[8:11], v[148:151], v[226:229], v[8:11]
	v_mfma_f32_16x16x32_bf16 v[0:3], v[156:159], v[226:229], v[0:3]
	v_mfma_f32_16x16x32_bf16 v[60:63], v[160:163], v[198:201], v[60:63]
	v_mfma_f32_16x16x32_bf16 v[52:55], v[168:171], v[198:201], v[52:55]
	v_mfma_f32_16x16x32_bf16 v[44:47], v[160:163], v[206:209], v[44:47]
	v_mfma_f32_16x16x32_bf16 v[36:39], v[168:171], v[206:209], v[36:39]
	v_mfma_f32_16x16x32_bf16 v[28:31], v[160:163], v[214:217], v[28:31]
	v_mfma_f32_16x16x32_bf16 v[20:23], v[168:171], v[214:217], v[20:23]
	v_mfma_f32_16x16x32_bf16 v[12:15], v[160:163], v[222:225], v[12:15]
	v_mfma_f32_16x16x32_bf16 v[4:7], v[168:171], v[222:225], v[4:7]
	v_mfma_f32_16x16x32_bf16 v[60:63], v[164:167], v[202:205], v[60:63]
	v_mfma_f32_16x16x32_bf16 v[52:55], v[172:175], v[202:205], v[52:55]
	v_mfma_f32_16x16x32_bf16 v[44:47], v[164:167], v[210:213], v[44:47]
	v_mfma_f32_16x16x32_bf16 v[36:39], v[172:175], v[210:213], v[36:39]
	v_mfma_f32_16x16x32_bf16 v[28:31], v[164:167], v[218:221], v[28:31]
	v_mfma_f32_16x16x32_bf16 v[20:23], v[172:175], v[218:221], v[20:23]
	v_mfma_f32_16x16x32_bf16 v[12:15], v[164:167], v[226:229], v[12:15]
	v_mfma_f32_16x16x32_bf16 v[4:7], v[172:175], v[226:229], v[4:7]
	s_setprio 0
	s_barrier
	s_add_i32 s30, 0, 0x18000
	s_add_i32 s31, 0, 0x1c000
	v_add_u32_e32 v156, s30, v145
	v_add_u32_e32 v172, s31, v145
	ds_read_b128 v[140:143], v156
	ds_read_b128 v[148:151], v156 offset:1024
	ds_read_b128 v[152:155], v156 offset:2048
	ds_read_b128 v[156:159], v156 offset:3072
	ds_read_b128 v[160:163], v172
	ds_read_b128 v[164:167], v172 offset:1024
	ds_read_b128 v[168:171], v172 offset:2048
	ds_read_b128 v[172:175], v172 offset:3072
	s_add_u32 s28, s28, 0x40000
	s_addc_u32 s29, s29, 0
	s_mov_b32 m0, s46
	v_lshl_add_u64 v[244:245], s[28:29], 0, v[134:135]
	ds_read_b128 v[198:201], v147 offset:32768
	ds_read_b128 v[202:205], v147 offset:33792
	ds_read_b128 v[206:209], v147 offset:34816
	ds_read_b128 v[210:213], v147 offset:35840
	ds_read_b128 v[214:217], v147 offset:36864
	ds_read_b128 v[218:221], v147 offset:37888
	ds_read_b128 v[222:225], v147 offset:38912
	ds_read_b128 v[226:229], v147 offset:39936
	global_load_lds_dwordx4 v[244:245], off
	v_lshl_add_u64 v[244:245], s[28:29], 0, v[132:133]
	s_mov_b32 m0, s47
	s_nop 0
	global_load_lds_dwordx4 v[244:245], off
	s_waitcnt vmcnt(8) lgkmcnt(0)
	s_barrier
	s_setprio 1
	v_mfma_f32_16x16x32_bf16 v[120:123], v[140:143], v[198:201], v[120:123]
	v_mfma_f32_16x16x32_bf16 v[112:115], v[152:155], v[198:201], v[112:115]
	v_mfma_f32_16x16x32_bf16 v[104:107], v[140:143], v[206:209], v[104:107]
	v_mfma_f32_16x16x32_bf16 v[96:99], v[152:155], v[206:209], v[96:99]
	v_mfma_f32_16x16x32_bf16 v[88:91], v[140:143], v[214:217], v[88:91]
	v_mfma_f32_16x16x32_bf16 v[80:83], v[152:155], v[214:217], v[80:83]
	v_mfma_f32_16x16x32_bf16 v[72:75], v[140:143], v[222:225], v[72:75]
	v_mfma_f32_16x16x32_bf16 v[64:67], v[152:155], v[222:225], v[64:67]
	v_mfma_f32_16x16x32_bf16 v[120:123], v[148:151], v[202:205], v[120:123]
	v_mfma_f32_16x16x32_bf16 v[112:115], v[156:159], v[202:205], v[112:115]
	v_mfma_f32_16x16x32_bf16 v[104:107], v[148:151], v[210:213], v[104:107]
	v_mfma_f32_16x16x32_bf16 v[96:99], v[156:159], v[210:213], v[96:99]
	v_mfma_f32_16x16x32_bf16 v[88:91], v[148:151], v[218:221], v[88:91]
	v_mfma_f32_16x16x32_bf16 v[80:83], v[156:159], v[218:221], v[80:83]
	v_mfma_f32_16x16x32_bf16 v[72:75], v[148:151], v[226:229], v[72:75]
	v_mfma_f32_16x16x32_bf16 v[64:67], v[156:159], v[226:229], v[64:67]
	v_mfma_f32_16x16x32_bf16 v[124:127], v[160:163], v[198:201], v[124:127]
	v_mfma_f32_16x16x32_bf16 v[116:119], v[168:171], v[198:201], v[116:119]
	v_mfma_f32_16x16x32_bf16 v[108:111], v[160:163], v[206:209], v[108:111]
	v_mfma_f32_16x16x32_bf16 v[100:103], v[168:171], v[206:209], v[100:103]
	v_mfma_f32_16x16x32_bf16 v[92:95], v[160:163], v[214:217], v[92:95]
	v_mfma_f32_16x16x32_bf16 v[84:87], v[168:171], v[214:217], v[84:87]
	v_mfma_f32_16x16x32_bf16 v[76:79], v[160:163], v[222:225], v[76:79]
	v_mfma_f32_16x16x32_bf16 v[68:71], v[168:171], v[222:225], v[68:71]
	v_mfma_f32_16x16x32_bf16 v[124:127], v[164:167], v[202:205], v[124:127]
	v_mfma_f32_16x16x32_bf16 v[116:119], v[172:175], v[202:205], v[116:119]
	v_mfma_f32_16x16x32_bf16 v[108:111], v[164:167], v[210:213], v[108:111]
	v_mfma_f32_16x16x32_bf16 v[100:103], v[172:175], v[210:213], v[100:103]
	v_mfma_f32_16x16x32_bf16 v[92:95], v[164:167], v[218:221], v[92:95]
	v_mfma_f32_16x16x32_bf16 v[84:87], v[172:175], v[218:221], v[84:87]
	v_mfma_f32_16x16x32_bf16 v[76:79], v[164:167], v[226:229], v[76:79]
	v_mfma_f32_16x16x32_bf16 v[68:71], v[172:175], v[226:229], v[68:71]
	s_setprio 0
	s_barrier
	s_add_i32 s28, s30, s45
	v_lshl_add_u64 v[176:177], v[176:177], 0, s[90:91]
	s_mov_b32 m0, s28
	ds_read_b128 v[198:201], v147 offset:49152
	ds_read_b128 v[202:205], v147 offset:50176
	ds_read_b128 v[206:209], v147 offset:51200
	ds_read_b128 v[210:213], v147 offset:52224
	ds_read_b128 v[214:217], v147 offset:53248
	ds_read_b128 v[218:221], v147 offset:54272
	ds_read_b128 v[222:225], v147 offset:55296
	ds_read_b128 v[226:229], v147 offset:56320
	global_load_lds_dwordx4 v[176:177], off
	s_add_i32 m0, s28, 0x2000
	s_add_u32 s26, s26, 0x40080
	v_lshl_add_u64 v[176:177], v[238:239], 0, s[90:91]
	s_addc_u32 s27, s27, 0
	s_add_i32 s28, s31, s45
	global_load_lds_dwordx4 v[176:177], off
	v_lshl_add_u64 v[176:177], s[26:27], 0, v[128:129]
	s_mov_b32 m0, s28
	s_nop 0
	global_load_lds_dwordx4 v[176:177], off
	v_lshl_add_u64 v[176:177], s[26:27], 0, v[130:131]
	s_add_i32 m0, s28, 0x2000
	s_nop 0
	global_load_lds_dwordx4 v[176:177], off
	v_lshl_add_u64 v[176:177], v[240:241], 0, s[90:91]
	s_mov_b32 m0, s0
	s_nop 0
	global_load_lds_dwordx4 v[176:177], off
	v_lshl_add_u64 v[176:177], v[242:243], 0, s[90:91]
	s_mov_b32 m0, s4
	s_nop 0
	global_load_lds_dwordx4 v[176:177], off
	s_waitcnt vmcnt(8) lgkmcnt(0)
	s_barrier
	s_setprio 1
	v_mfma_f32_16x16x32_bf16 v[56:59], v[140:143], v[198:201], v[56:59]
	v_mfma_f32_16x16x32_bf16 v[48:51], v[152:155], v[198:201], v[48:51]
	v_mfma_f32_16x16x32_bf16 v[40:43], v[140:143], v[206:209], v[40:43]
	v_mfma_f32_16x16x32_bf16 v[32:35], v[152:155], v[206:209], v[32:35]
	v_mfma_f32_16x16x32_bf16 v[24:27], v[140:143], v[214:217], v[24:27]
	v_mfma_f32_16x16x32_bf16 v[16:19], v[152:155], v[214:217], v[16:19]
	v_mfma_f32_16x16x32_bf16 v[8:11], v[140:143], v[222:225], v[8:11]
	v_mfma_f32_16x16x32_bf16 v[0:3], v[152:155], v[222:225], v[0:3]
	v_mfma_f32_16x16x32_bf16 v[56:59], v[148:151], v[202:205], v[56:59]
	v_mfma_f32_16x16x32_bf16 v[48:51], v[156:159], v[202:205], v[48:51]
	v_mfma_f32_16x16x32_bf16 v[40:43], v[148:151], v[210:213], v[40:43]
	v_mfma_f32_16x16x32_bf16 v[32:35], v[156:159], v[210:213], v[32:35]
	v_mfma_f32_16x16x32_bf16 v[24:27], v[148:151], v[218:221], v[24:27]
	v_mfma_f32_16x16x32_bf16 v[16:19], v[156:159], v[218:221], v[16:19]
	v_mfma_f32_16x16x32_bf16 v[8:11], v[148:151], v[226:229], v[8:11]
	v_mfma_f32_16x16x32_bf16 v[0:3], v[156:159], v[226:229], v[0:3]
	v_mfma_f32_16x16x32_bf16 v[60:63], v[160:163], v[198:201], v[60:63]
	v_mfma_f32_16x16x32_bf16 v[52:55], v[168:171], v[198:201], v[52:55]
	v_mfma_f32_16x16x32_bf16 v[44:47], v[160:163], v[206:209], v[44:47]
	v_mfma_f32_16x16x32_bf16 v[36:39], v[168:171], v[206:209], v[36:39]
	v_mfma_f32_16x16x32_bf16 v[28:31], v[160:163], v[214:217], v[28:31]
	v_mfma_f32_16x16x32_bf16 v[20:23], v[168:171], v[214:217], v[20:23]
	v_mfma_f32_16x16x32_bf16 v[12:15], v[160:163], v[222:225], v[12:15]
	v_mfma_f32_16x16x32_bf16 v[4:7], v[168:171], v[222:225], v[4:7]
	v_mfma_f32_16x16x32_bf16 v[60:63], v[164:167], v[202:205], v[60:63]
	v_mfma_f32_16x16x32_bf16 v[52:55], v[172:175], v[202:205], v[52:55]
	v_mfma_f32_16x16x32_bf16 v[44:47], v[164:167], v[210:213], v[44:47]
	v_mfma_f32_16x16x32_bf16 v[36:39], v[172:175], v[210:213], v[36:39]
	v_mfma_f32_16x16x32_bf16 v[28:31], v[164:167], v[218:221], v[28:31]
	v_mfma_f32_16x16x32_bf16 v[20:23], v[172:175], v[218:221], v[20:23]
	v_mfma_f32_16x16x32_bf16 v[12:15], v[164:167], v[226:229], v[12:15]
	v_mfma_f32_16x16x32_bf16 v[4:7], v[172:175], v[226:229], v[4:7]
	s_setprio 0
	s_barrier
	s_add_i32 s51, s51, 2
	s_add_u32 s49, s49, 0x100
	s_addc_u32 s50, s50, 0
	s_add_u32 s24, s24, 0x100
	s_addc_u32 s25, s25, 0
	s_cmp_gt_u32 s51, 13
	s_cbranch_scc0 .LBB0_638
	s_and_b64 vcc, exec, s[10:11]
	s_cbranch_vccz .LBB0_641
	s_barrier
